# v19 with hipcc's 80 per-segment s_setprio flips in the GEMM K-loops deleted (A/B of the flips)
# baseline (speedup 1.0000x reference)
; #define PG8_STAGE(bufoff, gbase, voff) do { _Pragma("unroll") for (int _i = 0; _i < 2; ++_i) \
;     __builtin_amdgcn_global_load_lds((const unsigned*)((const char*)(gbase) + (voff)[_i]), (PG8_LAS unsigned*)(lds + (bufoff) + ldsw + _i * 8192), 16, 0, 0); } while (0)
; #define PG8_LDA(dst, b, h) do { _Pragma("unroll") for (int m = 0; m < 4; ++m) _Pragma("unroll") for (int k = 0; k < 2; ++k) dst[m][k] = *(const PG8_LAS bf16x8*)(lds + PG8_SA(b, h) + aoff + m * 2048 + k * 1024); } while (0)
; #define PG8_LDB(dst, b, h) do { _Pragma("unroll") for (int n = 0; n < 2; ++n) _Pragma("unroll") for (int k = 0; k < 2; ++k) dst[n][k] = *(const PG8_LAS bf16x8*)(lds + PG8_SB(b, h) + boff + n * 2048 + k * 1024); } while (0)
; #define PG8_WAIT_V(n) asm volatile("s_waitcnt vmcnt(" #n ")" ::: "memory")
; template <class Epi>
; DI void gemm_phase(PG8_LAS unsigned char* lds, const Gemm g, const StaticOrder& S, const Epi& E) {
;     ...
;     for (int t = 0; t < nt; t += 2) {
;       const bool last = (t == nt - 2);
;       const char* a1 = cA + (size_t)(t + 1) * kstep;
;       const char* a2 = last ? nA : cA + (size_t)(t + 2) * kstep; const char* b2 = last ? nB : cB + (size_t)(t + 2) * kstep;
;       const char* a3 = a2 + kstep; const char* b3 = b2 + kstep;
;       PG8_LDB(B0, 0, 0); PG8_SCHED; PG8_LDA(At, 0, 0); PG8_STAGE(PG8_SA(1, 1), a1 + hstepA, voffA);
;       PG8_WAIT_L(8); PG8_BAR; PG8_WAIT_L(0); PG8_MMA(0, 0, At, B0); PG8_BAR; PG8_SCHED;
;       PG8_LDB(B1, 0, 1); PG8_STAGE(PG8_SB(0, 0), b2, voffB);
;       PG8_BAR; PG8_WAIT_L(0); PG8_MMA(0, 1, At, B1); PG8_BAR;
;       PG8_LDA(At, 0, 1); PG8_STAGE(PG8_SA(0, 0), a2, voffA);
;       PG8_BAR; PG8_WAIT_L(0); PG8_MMA(1, 0, At, B0); PG8_BAR; PG8_SCHED;
;       PG8_STAGE(PG8_SB(0, 1), b2 + hstepB, voffB);
;       PG8_WAIT_V(6); PG8_BAR; PG8_MMA(1, 1, At, B1); PG8_BAR;
;       PG8_LDB(B0, 1, 0); PG8_SCHED; PG8_LDA(At, 1, 0); PG8_STAGE(PG8_SA(0, 1), a2 + hstepA, voffA);
;       PG8_WAIT_L(8); PG8_BAR; PG8_WAIT_L(0); PG8_MMA(0, 0, At, B0); PG8_BAR; PG8_SCHED;
;       PG8_LDB(B1, 1, 1); PG8_STAGE(PG8_SB(1, 0), b3, voffB);
;       PG8_BAR; PG8_WAIT_L(0); PG8_MMA(0, 1, At, B1); PG8_BAR;
;       PG8_LDA(At, 1, 1); PG8_STAGE(PG8_SA(1, 0), a3, voffA);
;       PG8_BAR; PG8_WAIT_L(0); PG8_MMA(1, 0, At, B0); PG8_BAR; PG8_SCHED;
;       PG8_STAGE(PG8_SB(1, 1), b3 + hstepB, voffB);
;       PG8_WAIT_V(6); PG8_BAR; PG8_MMA(1, 1, At, B1); PG8_BAR;
.LBB0_116:
	s_add_u32 s70, s12, s0
	s_addc_u32 s71, s13, s1
	s_add_u32 s70, s70, 0x100
	s_addc_u32 s71, s71, 0
	s_add_u32 s90, s94, s0
	s_addc_u32 s91, s97, s1
	s_add_i32 vcc_hi, 0, 0x10000
	v_add_u32_e32 v153, vcc_hi, v150
	ds_read_b128 v[154:157], v153
	ds_read_b128 v[158:161], v153 offset:1024
	ds_read_b128 v[162:165], v153 offset:2048
	ds_read_b128 v[166:169], v153 offset:3072
	s_cmpk_eq_i32 s0, 0x700
	s_cselect_b32 s89, s17, s71
	s_cselect_b32 s88, s16, s70
	s_cselect_b32 s71, s15, s91
	s_cselect_b32 s70, s93, s90
	v_lshl_add_u64 v[202:203], v[148:149], 0, s[0:1]
	s_add_i32 m0, s85, 0xc000
	ds_read_b128 v[170:173], v152
	ds_read_b128 v[174:177], v152 offset:1024
	ds_read_b128 v[178:181], v152 offset:2048
	ds_read_b128 v[182:185], v152 offset:3072
	ds_read_b128 v[186:189], v152 offset:4096
	ds_read_b128 v[190:193], v152 offset:5120
	ds_read_b128 v[194:197], v152 offset:6144
	ds_read_b128 v[198:201], v152 offset:7168
	global_load_lds_dwordx4 v[202:203], off
	v_lshl_add_u64 v[202:203], v[140:141], 0, s[0:1]
	s_add_i32 m0, s85, 0xe000
	s_nop 0
	global_load_lds_dwordx4 v[202:203], off
	s_waitcnt lgkmcnt(8)
	s_barrier
	s_waitcnt lgkmcnt(0)
	s_waitcnt lgkmcnt(0)
	v_mfma_f32_16x16x32_bf16 v[126:129], v[154:157], v[170:173], v[126:129]
	v_mfma_f32_16x16x32_bf16 v[122:125], v[162:165], v[170:173], v[122:125]
	v_mfma_f32_16x16x32_bf16 v[118:121], v[154:157], v[178:181], v[118:121]
	v_mfma_f32_16x16x32_bf16 v[114:117], v[162:165], v[178:181], v[114:117]
	v_mfma_f32_16x16x32_bf16 v[102:105], v[154:157], v[186:189], v[102:105]
	v_mfma_f32_16x16x32_bf16 v[98:101], v[162:165], v[186:189], v[98:101]
	v_mfma_f32_16x16x32_bf16 v[86:89], v[154:157], v[194:197], v[86:89]
	v_mfma_f32_16x16x32_bf16 v[82:85], v[162:165], v[194:197], v[82:85]
	v_mfma_f32_16x16x32_bf16 v[126:129], v[158:161], v[174:177], v[126:129]
	v_mfma_f32_16x16x32_bf16 v[122:125], v[166:169], v[174:177], v[122:125]
	v_mfma_f32_16x16x32_bf16 v[118:121], v[158:161], v[182:185], v[118:121]
	v_mfma_f32_16x16x32_bf16 v[114:117], v[166:169], v[182:185], v[114:117]
	v_mfma_f32_16x16x32_bf16 v[102:105], v[158:161], v[190:193], v[102:105]
	v_mfma_f32_16x16x32_bf16 v[98:101], v[166:169], v[190:193], v[98:101]
	v_mfma_f32_16x16x32_bf16 v[86:89], v[158:161], v[198:201], v[86:89]
	v_mfma_f32_16x16x32_bf16 v[82:85], v[166:169], v[198:201], v[82:85]
	s_barrier
	s_add_i32 s96, 0, 0x14000
	s_add_i32 s90, vcc_hi, s76
	v_add_u32_e32 v153, s96, v150
	v_lshl_add_u64 v[206:207], s[70:71], 0, v[0:1]
	s_mov_b32 m0, s90
	ds_read_b128 v[202:205], v153
	ds_read_b128 v[226:229], v153 offset:1024
	ds_read_b128 v[230:233], v153 offset:2048
	ds_read_b128 v[234:237], v153 offset:3072
	global_load_lds_dwordx4 v[206:207], off
	v_lshl_add_u64 v[212:213], s[70:71], 0, v[130:131]
	s_add_i32 m0, s90, 0x2000
	s_nop 0
	global_load_lds_dwordx4 v[212:213], off
	s_barrier
	s_waitcnt lgkmcnt(0)
	s_waitcnt lgkmcnt(0)
	v_mfma_f32_16x16x32_bf16 v[110:113], v[202:205], v[170:173], v[110:113]
	v_mfma_f32_16x16x32_bf16 v[106:109], v[230:233], v[170:173], v[106:109]
	v_mfma_f32_16x16x32_bf16 v[94:97], v[202:205], v[178:181], v[94:97]
	v_mfma_f32_16x16x32_bf16 v[90:93], v[230:233], v[178:181], v[90:93]
	v_mfma_f32_16x16x32_bf16 v[78:81], v[202:205], v[186:189], v[78:81]
	v_mfma_f32_16x16x32_bf16 v[74:77], v[230:233], v[186:189], v[74:77]
	v_mfma_f32_16x16x32_bf16 v[70:73], v[202:205], v[194:197], v[70:73]
	v_mfma_f32_16x16x32_bf16 v[66:69], v[230:233], v[194:197], v[66:69]
	v_mfma_f32_16x16x32_bf16 v[110:113], v[226:229], v[174:177], v[110:113]
	v_mfma_f32_16x16x32_bf16 v[106:109], v[234:237], v[174:177], v[106:109]
	v_mfma_f32_16x16x32_bf16 v[94:97], v[226:229], v[182:185], v[94:97]
	v_mfma_f32_16x16x32_bf16 v[90:93], v[234:237], v[182:185], v[90:93]
	v_mfma_f32_16x16x32_bf16 v[78:81], v[226:229], v[190:193], v[78:81]
	v_mfma_f32_16x16x32_bf16 v[74:77], v[234:237], v[190:193], v[74:77]
	v_mfma_f32_16x16x32_bf16 v[70:73], v[226:229], v[198:201], v[70:73]
	v_mfma_f32_16x16x32_bf16 v[66:69], v[234:237], v[198:201], v[66:69]
	s_mov_b32 m0, s85
	v_lshl_add_u64 v[220:221], s[88:89], 0, v[134:135]
	s_barrier
	ds_read_b128 v[170:173], v152 offset:16384
	ds_read_b128 v[174:177], v152 offset:17408
	ds_read_b128 v[178:181], v152 offset:18432
	ds_read_b128 v[182:185], v152 offset:19456
	ds_read_b128 v[186:189], v152 offset:20480
	ds_read_b128 v[190:193], v152 offset:21504
	ds_read_b128 v[194:197], v152 offset:22528
	ds_read_b128 v[198:201], v152 offset:23552
	global_load_lds_dwordx4 v[220:221], off
	v_lshl_add_u64 v[238:239], s[88:89], 0, v[132:133]
	s_mov_b32 m0, s20
	s_nop 0
	global_load_lds_dwordx4 v[238:239], off
	s_barrier
	s_waitcnt lgkmcnt(0)
	s_waitcnt lgkmcnt(0)
	v_mfma_f32_16x16x32_bf16 v[62:65], v[154:157], v[170:173], v[62:65]
	v_mfma_f32_16x16x32_bf16 v[58:61], v[162:165], v[170:173], v[58:61]
	v_mfma_f32_16x16x32_bf16 v[54:57], v[154:157], v[178:181], v[54:57]
	v_mfma_f32_16x16x32_bf16 v[50:53], v[162:165], v[178:181], v[50:53]
	v_mfma_f32_16x16x32_bf16 v[38:41], v[154:157], v[186:189], v[38:41]
	v_mfma_f32_16x16x32_bf16 v[34:37], v[162:165], v[186:189], v[34:37]
	v_mfma_f32_16x16x32_bf16 v[22:25], v[154:157], v[194:197], v[22:25]
	v_mfma_f32_16x16x32_bf16 v[18:21], v[162:165], v[194:197], v[18:21]
	v_mfma_f32_16x16x32_bf16 v[62:65], v[158:161], v[174:177], v[62:65]
	v_mfma_f32_16x16x32_bf16 v[58:61], v[166:169], v[174:177], v[58:61]
	v_mfma_f32_16x16x32_bf16 v[54:57], v[158:161], v[182:185], v[54:57]
	v_mfma_f32_16x16x32_bf16 v[50:53], v[166:169], v[182:185], v[50:53]
	v_mfma_f32_16x16x32_bf16 v[38:41], v[158:161], v[190:193], v[38:41]
	v_mfma_f32_16x16x32_bf16 v[34:37], v[166:169], v[190:193], v[34:37]
	v_mfma_f32_16x16x32_bf16 v[22:25], v[158:161], v[198:201], v[22:25]
	v_mfma_f32_16x16x32_bf16 v[18:21], v[166:169], v[198:201], v[18:21]
	s_barrier
; #define PG8_STAGE(bufoff, gbase, voff) do { _Pragma("unroll") for (int _i = 0; _i < 2; ++_i) \
;     __builtin_amdgcn_global_load_lds((const unsigned*)((const char*)(gbase) + (voff)[_i]), (PG8_LAS unsigned*)(lds + (bufoff) + ldsw + _i * 8192), 16, 0, 0); } while (0)
; #define PG8_LDA(dst, b, h) do { _Pragma("unroll") for (int m = 0; m < 4; ++m) _Pragma("unroll") for (int k = 0; k < 2; ++k) dst[m][k] = *(const PG8_LAS bf16x8*)(lds + PG8_SA(b, h) + aoff + m * 2048 + k * 1024); } while (0)
; #define PG8_LDB(dst, b, h) do { _Pragma("unroll") for (int n = 0; n < 2; ++n) _Pragma("unroll") for (int k = 0; k < 2; ++k) dst[n][k] = *(const PG8_LAS bf16x8*)(lds + PG8_SB(b, h) + boff + n * 2048 + k * 1024); } while (0)
; #define PG8_WAIT_V(n) asm volatile("s_waitcnt vmcnt(" #n ")" ::: "memory")
; template <class Epi>
; DI void gemm_phase(PG8_LAS unsigned char* lds, const Gemm g, const StaticOrder& S, const Epi& E) {
;     ...
;     for (int t = 0; t < nt; t += 2) {
;       const bool last = (t == nt - 2);
;       const char* a1 = cA + (size_t)(t + 1) * kstep;
;       const char* a2 = last ? nA : cA + (size_t)(t + 2) * kstep; const char* b2 = last ? nB : cB + (size_t)(t + 2) * kstep;
;       const char* a3 = a2 + kstep; const char* b3 = b2 + kstep;
;       PG8_LDB(B0, 0, 0); PG8_SCHED; PG8_LDA(At, 0, 0); PG8_STAGE(PG8_SA(1, 1), a1 + hstepA, voffA);
;       PG8_WAIT_L(8); PG8_BAR; PG8_WAIT_L(0); PG8_MMA(0, 0, At, B0); PG8_BAR; PG8_SCHED;
;       PG8_LDB(B1, 0, 1); PG8_STAGE(PG8_SB(0, 0), b2, voffB);
;       PG8_BAR; PG8_WAIT_L(0); PG8_MMA(0, 1, At, B1); PG8_BAR;
;       PG8_LDA(At, 0, 1); PG8_STAGE(PG8_SA(0, 0), a2, voffA);
;       PG8_BAR; PG8_WAIT_L(0); PG8_MMA(1, 0, At, B0); PG8_BAR; PG8_SCHED;
;       PG8_STAGE(PG8_SB(0, 1), b2 + hstepB, voffB);
;       PG8_WAIT_V(6); PG8_BAR; PG8_MMA(1, 1, At, B1); PG8_BAR;
;       PG8_LDB(B0, 1, 0); PG8_SCHED; PG8_LDA(At, 1, 0); PG8_STAGE(PG8_SA(0, 1), a2 + hstepA, voffA);
;       PG8_WAIT_L(8); PG8_BAR; PG8_WAIT_L(0); PG8_MMA(0, 0, At, B0); PG8_BAR; PG8_SCHED;
;       PG8_LDB(B1, 1, 1); PG8_STAGE(PG8_SB(1, 0), b3, voffB);
;       PG8_BAR; PG8_WAIT_L(0); PG8_MMA(0, 1, At, B1); PG8_BAR;
;       PG8_LDA(At, 1, 1); PG8_STAGE(PG8_SA(1, 0), a3, voffA);
;       PG8_BAR; PG8_WAIT_L(0); PG8_MMA(1, 0, At, B0); PG8_BAR; PG8_SCHED;
;       PG8_STAGE(PG8_SB(1, 1), b3 + hstepB, voffB);
;       PG8_WAIT_V(6); PG8_BAR; PG8_MMA(1, 1, At, B1); PG8_BAR;
	s_add_u32 s90, s70, 0x40000
	s_addc_u32 s91, s71, 0
	s_add_i32 s96, s96, s76
	v_lshl_add_u64 v[154:155], s[90:91], 0, v[0:1]
	s_mov_b32 m0, s96
	s_nop 0
	global_load_lds_dwordx4 v[154:155], off
	v_lshl_add_u64 v[154:155], s[90:91], 0, v[130:131]
	s_add_i32 m0, s96, 0x2000
	s_nop 0
	global_load_lds_dwordx4 v[154:155], off
	s_waitcnt vmcnt(6)
	s_barrier
	v_mfma_f32_16x16x32_bf16 v[46:49], v[202:205], v[170:173], v[46:49]
	v_mfma_f32_16x16x32_bf16 v[42:45], v[230:233], v[170:173], v[42:45]
	v_mfma_f32_16x16x32_bf16 v[30:33], v[202:205], v[178:181], v[30:33]
	v_mfma_f32_16x16x32_bf16 v[26:29], v[230:233], v[178:181], v[26:29]
	v_mfma_f32_16x16x32_bf16 v[14:17], v[202:205], v[186:189], v[14:17]
	v_mfma_f32_16x16x32_bf16 v[10:13], v[230:233], v[186:189], v[10:13]
	v_mfma_f32_16x16x32_bf16 v[6:9], v[202:205], v[194:197], v[6:9]
	v_mfma_f32_16x16x32_bf16 v[2:5], v[230:233], v[194:197], v[2:5]
	v_mfma_f32_16x16x32_bf16 v[46:49], v[226:229], v[174:177], v[46:49]
	v_mfma_f32_16x16x32_bf16 v[42:45], v[234:237], v[174:177], v[42:45]
	v_mfma_f32_16x16x32_bf16 v[30:33], v[226:229], v[182:185], v[30:33]
	v_mfma_f32_16x16x32_bf16 v[26:29], v[234:237], v[182:185], v[26:29]
	v_mfma_f32_16x16x32_bf16 v[14:17], v[226:229], v[190:193], v[14:17]
	v_mfma_f32_16x16x32_bf16 v[10:13], v[234:237], v[190:193], v[10:13]
	v_mfma_f32_16x16x32_bf16 v[6:9], v[226:229], v[198:201], v[6:9]
	v_mfma_f32_16x16x32_bf16 v[2:5], v[234:237], v[198:201], v[2:5]
	s_add_i32 s90, 0, 0x18000
	v_add_u32_e32 v153, s90, v150
	s_barrier
	ds_read_b128 v[154:157], v153
	ds_read_b128 v[158:161], v153 offset:1024
	ds_read_b128 v[162:165], v153 offset:2048
	ds_read_b128 v[166:169], v153 offset:3072
	s_add_u32 s88, s88, s78
	s_addc_u32 s89, s89, 0
	s_mov_b32 m0, s21
	v_lshl_add_u64 v[202:203], s[88:89], 0, v[134:135]
	ds_read_b128 v[170:173], v152 offset:32768
	ds_read_b128 v[174:177], v152 offset:33792
	ds_read_b128 v[178:181], v152 offset:34816
	ds_read_b128 v[182:185], v152 offset:35840
	ds_read_b128 v[186:189], v152 offset:36864
	ds_read_b128 v[190:193], v152 offset:37888
	ds_read_b128 v[194:197], v152 offset:38912
	ds_read_b128 v[198:201], v152 offset:39936
	global_load_lds_dwordx4 v[202:203], off
	v_lshl_add_u64 v[202:203], s[88:89], 0, v[132:133]
	s_mov_b32 m0, s22
	s_nop 0
	global_load_lds_dwordx4 v[202:203], off
	s_waitcnt lgkmcnt(8)
	s_barrier
	s_waitcnt lgkmcnt(0)
	s_waitcnt lgkmcnt(0)
	v_mfma_f32_16x16x32_bf16 v[126:129], v[154:157], v[170:173], v[126:129]
	v_mfma_f32_16x16x32_bf16 v[122:125], v[162:165], v[170:173], v[122:125]
	v_mfma_f32_16x16x32_bf16 v[118:121], v[154:157], v[178:181], v[118:121]
	v_mfma_f32_16x16x32_bf16 v[114:117], v[162:165], v[178:181], v[114:117]
	v_mfma_f32_16x16x32_bf16 v[102:105], v[154:157], v[186:189], v[102:105]
	v_mfma_f32_16x16x32_bf16 v[98:101], v[162:165], v[186:189], v[98:101]
	v_mfma_f32_16x16x32_bf16 v[86:89], v[154:157], v[194:197], v[86:89]
	v_mfma_f32_16x16x32_bf16 v[82:85], v[162:165], v[194:197], v[82:85]
	v_mfma_f32_16x16x32_bf16 v[126:129], v[158:161], v[174:177], v[126:129]
	v_mfma_f32_16x16x32_bf16 v[122:125], v[166:169], v[174:177], v[122:125]
	v_mfma_f32_16x16x32_bf16 v[118:121], v[158:161], v[182:185], v[118:121]
	v_mfma_f32_16x16x32_bf16 v[114:117], v[166:169], v[182:185], v[114:117]
	v_mfma_f32_16x16x32_bf16 v[102:105], v[158:161], v[190:193], v[102:105]
	v_mfma_f32_16x16x32_bf16 v[98:101], v[166:169], v[190:193], v[98:101]
	v_mfma_f32_16x16x32_bf16 v[86:89], v[158:161], v[198:201], v[86:89]
	v_mfma_f32_16x16x32_bf16 v[82:85], v[166:169], v[198:201], v[82:85]
	s_barrier
	s_add_i32 s88, 0, 0x1c000
	s_add_i32 s89, s90, s76
	v_add_u32_e32 v153, s88, v150
	v_lshl_add_u64 v[206:207], v[206:207], 0, s[82:83]
	s_mov_b32 m0, s89
	ds_read_b128 v[202:205], v153
	ds_read_b128 v[226:229], v153 offset:1024
	ds_read_b128 v[230:233], v153 offset:2048
	ds_read_b128 v[234:237], v153 offset:3072
	global_load_lds_dwordx4 v[206:207], off
	v_lshl_add_u64 v[206:207], v[212:213], 0, s[82:83]
	s_add_i32 m0, s89, 0x2000
	s_nop 0
	global_load_lds_dwordx4 v[206:207], off
	s_barrier
	s_waitcnt lgkmcnt(0)
	s_waitcnt lgkmcnt(0)
	v_mfma_f32_16x16x32_bf16 v[110:113], v[202:205], v[170:173], v[110:113]
	v_mfma_f32_16x16x32_bf16 v[106:109], v[230:233], v[170:173], v[106:109]
	v_mfma_f32_16x16x32_bf16 v[94:97], v[202:205], v[178:181], v[94:97]
	v_mfma_f32_16x16x32_bf16 v[90:93], v[230:233], v[178:181], v[90:93]
	v_mfma_f32_16x16x32_bf16 v[78:81], v[202:205], v[186:189], v[78:81]
	v_mfma_f32_16x16x32_bf16 v[74:77], v[230:233], v[186:189], v[74:77]
	v_mfma_f32_16x16x32_bf16 v[70:73], v[202:205], v[194:197], v[70:73]
	v_mfma_f32_16x16x32_bf16 v[66:69], v[230:233], v[194:197], v[66:69]
	v_mfma_f32_16x16x32_bf16 v[110:113], v[226:229], v[174:177], v[110:113]
	v_mfma_f32_16x16x32_bf16 v[106:109], v[234:237], v[174:177], v[106:109]
	v_mfma_f32_16x16x32_bf16 v[94:97], v[226:229], v[182:185], v[94:97]
	v_mfma_f32_16x16x32_bf16 v[90:93], v[234:237], v[182:185], v[90:93]
	v_mfma_f32_16x16x32_bf16 v[78:81], v[226:229], v[190:193], v[78:81]
	v_mfma_f32_16x16x32_bf16 v[74:77], v[234:237], v[190:193], v[74:77]
	v_mfma_f32_16x16x32_bf16 v[70:73], v[226:229], v[198:201], v[70:73]
	v_mfma_f32_16x16x32_bf16 v[66:69], v[234:237], v[198:201], v[66:69]
	s_mov_b32 m0, s24
	v_lshl_add_u64 v[206:207], v[220:221], 0, s[82:83]
	s_barrier
	ds_read_b128 v[170:173], v152 offset:49152
	ds_read_b128 v[174:177], v152 offset:50176
	ds_read_b128 v[178:181], v152 offset:51200
	ds_read_b128 v[182:185], v152 offset:52224
	ds_read_b128 v[186:189], v152 offset:53248
	ds_read_b128 v[190:193], v152 offset:54272
	ds_read_b128 v[194:197], v152 offset:55296
	ds_read_b128 v[198:201], v152 offset:56320
	global_load_lds_dwordx4 v[206:207], off
	v_lshl_add_u64 v[206:207], v[238:239], 0, s[82:83]
	s_mov_b32 m0, s25
	s_nop 0
	global_load_lds_dwordx4 v[206:207], off
	s_barrier
; #define PG8_STAGE(bufoff, gbase, voff) do { _Pragma("unroll") for (int _i = 0; _i < 2; ++_i) \
;     __builtin_amdgcn_global_load_lds((const unsigned*)((const char*)(gbase) + (voff)[_i]), (PG8_LAS unsigned*)(lds + (bufoff) + ldsw + _i * 8192), 16, 0, 0); } while (0)
; #define PG8_LDA(dst, b, h) do { _Pragma("unroll") for (int m = 0; m < 4; ++m) _Pragma("unroll") for (int k = 0; k < 2; ++k) dst[m][k] = *(const PG8_LAS bf16x8*)(lds + PG8_SA(b, h) + aoff + m * 2048 + k * 1024); } while (0)
; #define PG8_LDB(dst, b, h) do { _Pragma("unroll") for (int n = 0; n < 2; ++n) _Pragma("unroll") for (int k = 0; k < 2; ++k) dst[n][k] = *(const PG8_LAS bf16x8*)(lds + PG8_SB(b, h) + boff + n * 2048 + k * 1024); } while (0)
; #define PG8_WAIT_V(n) asm volatile("s_waitcnt vmcnt(" #n ")" ::: "memory")
; template <class Epi>
; DI void gemm_phase(PG8_LAS unsigned char* lds, const Gemm g, const StaticOrder& S, const Epi& E) {
;     ...
;     for (int t = 0; t < nt; t += 2) {
;       const bool last = (t == nt - 2);
;       const char* a1 = cA + (size_t)(t + 1) * kstep;
;       const char* a2 = last ? nA : cA + (size_t)(t + 2) * kstep; const char* b2 = last ? nB : cB + (size_t)(t + 2) * kstep;
;       const char* a3 = a2 + kstep; const char* b3 = b2 + kstep;
;       PG8_LDB(B0, 0, 0); PG8_SCHED; PG8_LDA(At, 0, 0); PG8_STAGE(PG8_SA(1, 1), a1 + hstepA, voffA);
;       PG8_WAIT_L(8); PG8_BAR; PG8_WAIT_L(0); PG8_MMA(0, 0, At, B0); PG8_BAR; PG8_SCHED;
;       PG8_LDB(B1, 0, 1); PG8_STAGE(PG8_SB(0, 0), b2, voffB);
;       PG8_BAR; PG8_WAIT_L(0); PG8_MMA(0, 1, At, B1); PG8_BAR;
;       PG8_LDA(At, 0, 1); PG8_STAGE(PG8_SA(0, 0), a2, voffA);
;       PG8_BAR; PG8_WAIT_L(0); PG8_MMA(1, 0, At, B0); PG8_BAR; PG8_SCHED;
;       PG8_STAGE(PG8_SB(0, 1), b2 + hstepB, voffB);
;       PG8_WAIT_V(6); PG8_BAR; PG8_MMA(1, 1, At, B1); PG8_BAR;
;       PG8_LDB(B0, 1, 0); PG8_SCHED; PG8_LDA(At, 1, 0); PG8_STAGE(PG8_SA(0, 1), a2 + hstepA, voffA);
;       PG8_WAIT_L(8); PG8_BAR; PG8_WAIT_L(0); PG8_MMA(0, 0, At, B0); PG8_BAR; PG8_SCHED;
;       PG8_LDB(B1, 1, 1); PG8_STAGE(PG8_SB(1, 0), b3, voffB);
;       PG8_BAR; PG8_WAIT_L(0); PG8_MMA(0, 1, At, B1); PG8_BAR;
;       PG8_LDA(At, 1, 1); PG8_STAGE(PG8_SA(1, 0), a3, voffA);
;       PG8_BAR; PG8_WAIT_L(0); PG8_MMA(1, 0, At, B0); PG8_BAR; PG8_SCHED;
;       PG8_STAGE(PG8_SB(1, 1), b3 + hstepB, voffB);
;       PG8_WAIT_V(6); PG8_BAR; PG8_MMA(1, 1, At, B1); PG8_BAR;
	s_waitcnt lgkmcnt(0)
	s_waitcnt lgkmcnt(0)
	v_mfma_f32_16x16x32_bf16 v[62:65], v[154:157], v[170:173], v[62:65]
	v_mfma_f32_16x16x32_bf16 v[58:61], v[162:165], v[170:173], v[58:61]
	v_mfma_f32_16x16x32_bf16 v[54:57], v[154:157], v[178:181], v[54:57]
	v_mfma_f32_16x16x32_bf16 v[50:53], v[162:165], v[178:181], v[50:53]
	v_mfma_f32_16x16x32_bf16 v[38:41], v[154:157], v[186:189], v[38:41]
	v_mfma_f32_16x16x32_bf16 v[34:37], v[162:165], v[186:189], v[34:37]
	v_mfma_f32_16x16x32_bf16 v[22:25], v[154:157], v[194:197], v[22:25]
	v_mfma_f32_16x16x32_bf16 v[18:21], v[162:165], v[194:197], v[18:21]
	v_mfma_f32_16x16x32_bf16 v[62:65], v[158:161], v[174:177], v[62:65]
	v_mfma_f32_16x16x32_bf16 v[58:61], v[166:169], v[174:177], v[58:61]
	v_mfma_f32_16x16x32_bf16 v[54:57], v[158:161], v[182:185], v[54:57]
	v_mfma_f32_16x16x32_bf16 v[50:53], v[166:169], v[182:185], v[50:53]
	v_mfma_f32_16x16x32_bf16 v[38:41], v[158:161], v[190:193], v[38:41]
	v_mfma_f32_16x16x32_bf16 v[34:37], v[166:169], v[190:193], v[34:37]
	v_mfma_f32_16x16x32_bf16 v[22:25], v[158:161], v[198:201], v[22:25]
	v_mfma_f32_16x16x32_bf16 v[18:21], v[166:169], v[198:201], v[18:21]
	s_barrier
	s_add_u32 s70, s70, 0x40080
	s_addc_u32 s71, s71, 0
	s_add_i32 s88, s88, s76
	v_lshl_add_u64 v[154:155], s[70:71], 0, v[0:1]
	s_mov_b32 m0, s88
	s_nop 0
	global_load_lds_dwordx4 v[154:155], off
	v_lshl_add_u64 v[154:155], s[70:71], 0, v[130:131]
	s_add_i32 m0, s88, 0x2000
	s_nop 0
	global_load_lds_dwordx4 v[154:155], off
	s_waitcnt vmcnt(6)
	s_barrier
	v_mfma_f32_16x16x32_bf16 v[46:49], v[202:205], v[170:173], v[46:49]
	v_mfma_f32_16x16x32_bf16 v[42:45], v[230:233], v[170:173], v[42:45]
	v_mfma_f32_16x16x32_bf16 v[30:33], v[202:205], v[178:181], v[30:33]
	v_mfma_f32_16x16x32_bf16 v[26:29], v[230:233], v[178:181], v[26:29]
	v_mfma_f32_16x16x32_bf16 v[14:17], v[202:205], v[186:189], v[14:17]
	v_mfma_f32_16x16x32_bf16 v[10:13], v[230:233], v[186:189], v[10:13]
	v_mfma_f32_16x16x32_bf16 v[6:9], v[202:205], v[194:197], v[6:9]
	v_mfma_f32_16x16x32_bf16 v[2:5], v[230:233], v[194:197], v[2:5]
	v_mfma_f32_16x16x32_bf16 v[46:49], v[226:229], v[174:177], v[46:49]
	v_mfma_f32_16x16x32_bf16 v[42:45], v[234:237], v[174:177], v[42:45]
	v_mfma_f32_16x16x32_bf16 v[30:33], v[226:229], v[182:185], v[30:33]
	v_mfma_f32_16x16x32_bf16 v[26:29], v[234:237], v[182:185], v[26:29]
	v_mfma_f32_16x16x32_bf16 v[14:17], v[226:229], v[190:193], v[14:17]
	v_mfma_f32_16x16x32_bf16 v[10:13], v[234:237], v[190:193], v[10:13]
	v_mfma_f32_16x16x32_bf16 v[6:9], v[226:229], v[198:201], v[6:9]
	v_mfma_f32_16x16x32_bf16 v[2:5], v[234:237], v[198:201], v[2:5]
	s_add_i32 vcc_lo, vcc_lo, 2
	s_add_u32 s0, s0, 0x100
	s_addc_u32 s1, s1, 0
	s_cmp_gt_u32 vcc_lo, 13
	s_barrier
	s_cbranch_scc0 .LBB0_116
; DI unsigned pk2(float lo, float hi) { f32x2 v = {lo, hi}; return __builtin_bit_cast(unsigned, __builtin_convertvector(v, bf16x2v)); }
; #define PG8_WAIT_V(n) asm volatile("s_waitcnt vmcnt(" #n ")" ::: "memory")
; #define PG8_BAR __builtin_amdgcn_s_barrier()
; template <class Epi>
; DI void gemm_phase(PG8_LAS unsigned char* lds, const Gemm g, const StaticOrder& S, const Epi& E) {
;     ...
;     E(acc, cur, wr, wc, fr, fq);
;     if (!has_next) break;
; #pragma unroll
;     for (int a = 0; a < 2; ++a)
; #pragma unroll
;       for (int b = 0; b < 2; ++b)
; #pragma unroll
;         for (int m = 0; m < 4; ++m)
; #pragma unroll
;           for (int n = 0; n < 2; ++n) acc[a][b][m][n] = (f32x4){0.f, 0.f, 0.f, 0.f};
;     cur = nxt; cA = nA; cB = nB; ++ui;
;   }
;   PG8_WAIT_V(0);
;   if (wr == 0) PG8_BAR;
;   PG8_BAR;
;   DI void operator()(const f32x4 (&acc)[2][2][4][2], const pg8::Unit& un, int wr, int wc, int fr, int fq) const {
;     constexpr bool isA = (MODE == 0);
;     constexpr int NW = isA ? 2560 : 4096, kend = isA ? 1280 : 2048, vend = isA ? 1536 : 3072;
;     const int upm = un.pm + pm_off, upn = un.pn + pn_off;
;     const bool isctx = upm >= 256;
; #pragma unroll
;     for (int ai = 0; ai < 2; ++ai)
; #pragma unroll
;       for (int m = 0; m < 4; ++m) {
;         const int row = upm * 256 + ai * 128 + wr * 64 + m * 16 + fr;
; #pragma unroll
;         for (int bj = 0; bj < 2; ++bj) {
;           const int c128 = upn * 256 + bj * 128;
;           const int col0 = c128 + wc * 32 + fq * 8;
;           f32x4 v0 = acc[ai][bj][m][0], v1 = acc[ai][bj][m][1];
;           if (MODE == 2) {
;             u32x4 w; w[0] = pk2(v0[0], v0[1]); w[1] = pk2(v0[2], v0[3]); w[2] = pk2(v1[0], v1[1]); w[3] = pk2(v1[2], v1[3]);
;             *(u32x4*)(u + (size_t)row * 1024 + col0) = w;
	v_lshl_add_u32 v140, s27, 8, v142
	v_cvt_pk_bf16_f32 v70, v70, v71
	v_cvt_pk_bf16_f32 v71, v72, v73
	v_cvt_pk_bf16_f32 v72, v66, v67
	v_add_u32_e32 v66, 0x80, v140
	v_lshl_or_b32 v148, s86, 8, v151
	v_ashrrev_i32_e32 v141, 31, v140
	v_ashrrev_i32_e32 v67, 31, v66
	v_lshlrev_b64 v[154:155], 11, v[140:141]
	v_ashrrev_i32_e32 v149, 31, v148
	v_lshlrev_b64 v[66:67], 11, v[66:67]
	v_cvt_pk_bf16_f32 v126, v126, v127
	v_cvt_pk_bf16_f32 v127, v128, v129
	v_cvt_pk_bf16_f32 v128, v122, v123
	v_cvt_pk_bf16_f32 v129, v124, v125
	v_lshl_add_u64 v[122:123], s[36:37], 0, v[154:155]
	v_lshlrev_b64 v[124:125], 1, v[148:149]
	v_cvt_pk_bf16_f32 v110, v110, v111
	v_cvt_pk_bf16_f32 v111, v112, v113
	v_cvt_pk_bf16_f32 v112, v106, v107
	v_or_b32_e32 v106, 16, v140
	v_cvt_pk_bf16_f32 v62, v62, v63
	v_cvt_pk_bf16_f32 v63, v64, v65
	v_cvt_pk_bf16_f32 v64, v58, v59
	v_lshl_add_u64 v[58:59], s[36:37], 0, v[66:67]
	v_cvt_pk_bf16_f32 v46, v46, v47
	v_cvt_pk_bf16_f32 v47, v48, v49
	v_cvt_pk_bf16_f32 v48, v42, v43
	v_add_u32_e32 v42, 0x90, v140
	v_lshl_add_u64 v[122:123], v[122:123], 0, v[124:125]
	v_cvt_pk_bf16_f32 v113, v108, v109
	v_ashrrev_i32_e32 v107, 31, v106
	v_lshl_add_u64 v[58:59], v[58:59], 0, v[124:125]
	v_cvt_pk_bf16_f32 v49, v44, v45
	v_ashrrev_i32_e32 v43, 31, v42
	global_store_dwordx4 v[122:123], v[110:113], off offset:256
	global_store_dwordx4 v[58:59], v[46:49], off offset:256
	v_cvt_pk_bf16_f32 v94, v94, v95
	v_lshlrev_b64 v[110:111], 11, v[106:107]
	v_lshlrev_b64 v[46:47], 11, v[42:43]
	v_lshl_add_u64 v[110:111], s[36:37], 0, v[110:111]
	v_cvt_pk_bf16_f32 v95, v96, v97
	v_cvt_pk_bf16_f32 v96, v90, v91
	v_or_b32_e32 v90, 32, v140
	v_lshl_add_u64 v[46:47], s[36:37], 0, v[46:47]
	v_cvt_pk_bf16_f32 v30, v30, v31
	v_cvt_pk_bf16_f32 v31, v32, v33
	v_cvt_pk_bf16_f32 v32, v26, v27
	v_add_u32_e32 v26, 0xa0, v140
	v_lshl_add_u64 v[110:111], v[110:111], 0, v[124:125]
	v_cvt_pk_bf16_f32 v97, v92, v93
	v_ashrrev_i32_e32 v91, 31, v90
	v_lshl_add_u64 v[46:47], v[46:47], 0, v[124:125]
	v_cvt_pk_bf16_f32 v33, v28, v29
	v_ashrrev_i32_e32 v27, 31, v26
	global_store_dwordx4 v[110:111], v[94:97], off offset:256
	global_store_dwordx4 v[46:47], v[30:33], off offset:256
	v_cvt_pk_bf16_f32 v78, v78, v79
	v_lshlrev_b64 v[94:95], 11, v[90:91]
	v_lshlrev_b64 v[30:31], 11, v[26:27]
	v_lshl_add_u64 v[94:95], s[36:37], 0, v[94:95]
	v_cvt_pk_bf16_f32 v79, v80, v81
	v_cvt_pk_bf16_f32 v80, v74, v75
	v_or_b32_e32 v74, 48, v140
	v_lshl_add_u64 v[30:31], s[36:37], 0, v[30:31]
	v_cvt_pk_bf16_f32 v14, v14, v15
	v_cvt_pk_bf16_f32 v15, v16, v17
	v_cvt_pk_bf16_f32 v16, v10, v11
	v_add_u32_e32 v10, 0xb0, v140
	v_lshl_add_u64 v[94:95], v[94:95], 0, v[124:125]
	v_cvt_pk_bf16_f32 v81, v76, v77
	v_ashrrev_i32_e32 v75, 31, v74
	v_lshl_add_u64 v[30:31], v[30:31], 0, v[124:125]
	v_cvt_pk_bf16_f32 v17, v12, v13
	v_ashrrev_i32_e32 v11, 31, v10
	global_store_dwordx4 v[94:95], v[78:81], off offset:256
	global_store_dwordx4 v[30:31], v[14:17], off offset:256
	v_cvt_pk_bf16_f32 v106, v118, v119
	v_lshlrev_b64 v[78:79], 11, v[74:75]
	v_lshlrev_b64 v[14:15], 11, v[10:11]
	v_lshl_add_u64 v[78:79], s[36:37], 0, v[78:79]
	v_lshl_add_u64 v[14:15], s[36:37], 0, v[14:15]
	v_cvt_pk_bf16_f32 v107, v120, v121
	v_cvt_pk_bf16_f32 v108, v114, v115
	v_cvt_pk_bf16_f32 v109, v116, v117
	v_cvt_pk_bf16_f32 v90, v102, v103
	v_cvt_pk_bf16_f32 v91, v104, v105
	v_cvt_pk_bf16_f32 v92, v98, v99
	v_cvt_pk_bf16_f32 v93, v100, v101
	v_cvt_pk_bf16_f32 v74, v86, v87
	v_cvt_pk_bf16_f32 v75, v88, v89
	v_cvt_pk_bf16_f32 v76, v82, v83
	v_cvt_pk_bf16_f32 v77, v84, v85
	v_lshl_add_u64 v[78:79], v[78:79], 0, v[124:125]
	v_cvt_pk_bf16_f32 v73, v68, v69
	v_cvt_pk_bf16_f32 v65, v60, v61
	v_cvt_pk_bf16_f32 v42, v54, v55
	v_cvt_pk_bf16_f32 v43, v56, v57
	v_cvt_pk_bf16_f32 v44, v50, v51
	v_cvt_pk_bf16_f32 v45, v52, v53
	v_cvt_pk_bf16_f32 v26, v38, v39
	v_cvt_pk_bf16_f32 v27, v40, v41
	v_cvt_pk_bf16_f32 v28, v34, v35
	v_cvt_pk_bf16_f32 v29, v36, v37
	v_cvt_pk_bf16_f32 v10, v22, v23
	v_cvt_pk_bf16_f32 v11, v24, v25
	v_cvt_pk_bf16_f32 v12, v18, v19
	v_cvt_pk_bf16_f32 v13, v20, v21
	v_lshl_add_u64 v[14:15], v[14:15], 0, v[124:125]
	v_cvt_pk_bf16_f32 v6, v6, v7
	v_cvt_pk_bf16_f32 v7, v8, v9
	v_cvt_pk_bf16_f32 v8, v2, v3
	v_cvt_pk_bf16_f32 v9, v4, v5
	s_and_b64 vcc, exec, s[6:7]
	s_mov_b32 s86, s14
	s_mov_b32 s27, s87
	s_mov_b64 s[70:71], s[18:19]
	s_mov_b64 s[12:13], s[16:17]
	s_mov_b32 s95, s5
	s_movk_i32 s91, 0x1000
	s_movk_i32 s90, 0x2000
	s_mov_b32 s96, 0x800000
	s_movk_i32 s97, 0x104
	s_mov_b32 s94, 0x3e38aa3b
	global_store_dwordx4 v[122:123], v[126:129], off
	global_store_dwordx4 v[110:111], v[106:109], off
	global_store_dwordx4 v[94:95], v[90:93], off
	global_store_dwordx4 v[78:79], v[74:77], off
	global_store_dwordx4 v[78:79], v[70:73], off offset:256
	global_store_dwordx4 v[58:59], v[62:65], off
	global_store_dwordx4 v[46:47], v[42:45], off
	global_store_dwordx4 v[30:31], v[26:29], off
	global_store_dwordx4 v[14:15], v[10:13], off
	global_store_dwordx4 v[14:15], v[6:9], off offset:256
	s_cbranch_vccz .LBB0_111
	s_waitcnt vmcnt(0)
	s_cmpk_gt_u32 s2, 0xff
	v_readlane_b32 s69, v255, 54
	s_cbranch_scc1 .LBB0_120
	s_barrier

; #define PG8_STAGE(bufoff, gbase, voff) do { _Pragma("unroll") for (int _i = 0; _i < 2; ++_i) \
;     __builtin_amdgcn_global_load_lds((const unsigned*)((const char*)(gbase) + (voff)[_i]), (PG8_LAS unsigned*)(lds + (bufoff) + ldsw + _i * 8192), 16, 0, 0); } while (0)
; #define PG8_LDA(dst, b, h) do { _Pragma("unroll") for (int m = 0; m < 4; ++m) _Pragma("unroll") for (int k = 0; k < 2; ++k) dst[m][k] = *(const PG8_LAS bf16x8*)(lds + PG8_SA(b, h) + aoff + m * 2048 + k * 1024); } while (0)
; #define PG8_LDB(dst, b, h) do { _Pragma("unroll") for (int n = 0; n < 2; ++n) _Pragma("unroll") for (int k = 0; k < 2; ++k) dst[n][k] = *(const PG8_LAS bf16x8*)(lds + PG8_SB(b, h) + boff + n * 2048 + k * 1024); } while (0)
; #define PG8_WAIT_V(n) asm volatile("s_waitcnt vmcnt(" #n ")" ::: "memory")
; template <class Epi>
; DI void gemm_phase(PG8_LAS unsigned char* lds, const Gemm g, const StaticOrder& S, const Epi& E) {
;     ...
;     for (int t = 0; t < nt; t += 2) {
;       const bool last = (t == nt - 2);
;       const char* a1 = cA + (size_t)(t + 1) * kstep;
;       const char* a2 = last ? nA : cA + (size_t)(t + 2) * kstep; const char* b2 = last ? nB : cB + (size_t)(t + 2) * kstep;
;       const char* a3 = a2 + kstep; const char* b3 = b2 + kstep;
;       PG8_LDB(B0, 0, 0); PG8_SCHED; PG8_LDA(At, 0, 0); PG8_STAGE(PG8_SA(1, 1), a1 + hstepA, voffA);
;       PG8_WAIT_L(8); PG8_BAR; PG8_WAIT_L(0); PG8_MMA(0, 0, At, B0); PG8_BAR; PG8_SCHED;
;       PG8_LDB(B1, 0, 1); PG8_STAGE(PG8_SB(0, 0), b2, voffB);
;       PG8_BAR; PG8_WAIT_L(0); PG8_MMA(0, 1, At, B1); PG8_BAR;
;       PG8_LDA(At, 0, 1); PG8_STAGE(PG8_SA(0, 0), a2, voffA);
;       PG8_BAR; PG8_WAIT_L(0); PG8_MMA(1, 0, At, B0); PG8_BAR; PG8_SCHED;
;       PG8_STAGE(PG8_SB(0, 1), b2 + hstepB, voffB);
;       PG8_WAIT_V(6); PG8_BAR; PG8_MMA(1, 1, At, B1); PG8_BAR;
;       PG8_LDB(B0, 1, 0); PG8_SCHED; PG8_LDA(At, 1, 0); PG8_STAGE(PG8_SA(0, 1), a2 + hstepA, voffA);
;       PG8_WAIT_L(8); PG8_BAR; PG8_WAIT_L(0); PG8_MMA(0, 0, At, B0); PG8_BAR; PG8_SCHED;
;       PG8_LDB(B1, 1, 1); PG8_STAGE(PG8_SB(1, 0), b3, voffB);
;       PG8_BAR; PG8_WAIT_L(0); PG8_MMA(0, 1, At, B1); PG8_BAR;
;       PG8_LDA(At, 1, 1); PG8_STAGE(PG8_SA(1, 0), a3, voffA);
;       PG8_BAR; PG8_WAIT_L(0); PG8_MMA(1, 0, At, B0); PG8_BAR; PG8_SCHED;
;       PG8_STAGE(PG8_SB(1, 1), b3 + hstepB, voffB);
;       PG8_WAIT_V(6); PG8_BAR; PG8_MMA(1, 1, At, B1); PG8_BAR;
.LBB0_220:
	s_add_u32 s10, s8, 0xfffc0080
	s_addc_u32 s11, s9, -1
	s_add_i32 s26, 0, 0x10000
	v_add_u32_e32 v162, s26, v160
	ds_read_b128 v[130:133], v162
	ds_read_b128 v[134:137], v162 offset:1024
	ds_read_b128 v[156:159], v162 offset:2048
	ds_read_b128 v[162:165], v162 offset:3072
	s_cmp_eq_u32 s25, 12
	s_cselect_b32 s19, s13, s11
	s_cselect_b32 s18, s21, s10
	s_cselect_b32 s11, s1, s24
	s_cselect_b32 s10, s22, s23
	v_lshl_add_u64 v[198:199], s[8:9], 0, v[152:153]
	s_add_i32 m0, s35, 0xc000
	ds_read_b128 v[166:169], v161
	ds_read_b128 v[170:173], v161 offset:1024
	ds_read_b128 v[174:177], v161 offset:2048
	ds_read_b128 v[178:181], v161 offset:3072
	ds_read_b128 v[182:185], v161 offset:4096
	ds_read_b128 v[186:189], v161 offset:5120
	ds_read_b128 v[190:193], v161 offset:6144
	ds_read_b128 v[194:197], v161 offset:7168
	global_load_lds_dwordx4 v[198:199], off
	v_lshl_add_u64 v[198:199], s[8:9], 0, v[154:155]
	s_add_i32 m0, s35, 0xe000
	s_nop 0
	global_load_lds_dwordx4 v[198:199], off
	s_waitcnt lgkmcnt(8)
	s_barrier
	s_waitcnt lgkmcnt(0)
	s_waitcnt lgkmcnt(0)
	v_mfma_f32_16x16x32_bf16 v[126:129], v[130:133], v[166:169], v[126:129]
	v_mfma_f32_16x16x32_bf16 v[122:125], v[156:159], v[166:169], v[122:125]
	v_mfma_f32_16x16x32_bf16 v[110:113], v[130:133], v[174:177], v[110:113]
	v_mfma_f32_16x16x32_bf16 v[106:109], v[156:159], v[174:177], v[106:109]
	v_mfma_f32_16x16x32_bf16 v[94:97], v[130:133], v[182:185], v[94:97]
	v_mfma_f32_16x16x32_bf16 v[90:93], v[156:159], v[182:185], v[90:93]
	v_mfma_f32_16x16x32_bf16 v[78:81], v[130:133], v[190:193], v[78:81]
	v_mfma_f32_16x16x32_bf16 v[74:77], v[156:159], v[190:193], v[74:77]
	v_mfma_f32_16x16x32_bf16 v[126:129], v[134:137], v[170:173], v[126:129]
	v_mfma_f32_16x16x32_bf16 v[122:125], v[162:165], v[170:173], v[122:125]
	v_mfma_f32_16x16x32_bf16 v[110:113], v[134:137], v[178:181], v[110:113]
	v_mfma_f32_16x16x32_bf16 v[106:109], v[162:165], v[178:181], v[106:109]
	v_mfma_f32_16x16x32_bf16 v[94:97], v[134:137], v[186:189], v[94:97]
	v_mfma_f32_16x16x32_bf16 v[90:93], v[162:165], v[186:189], v[90:93]
	v_mfma_f32_16x16x32_bf16 v[78:81], v[134:137], v[194:197], v[78:81]
	v_mfma_f32_16x16x32_bf16 v[74:77], v[162:165], v[194:197], v[74:77]
	s_barrier
	s_add_i32 s33, 0, 0x14000
	v_add_u32_e32 v206, s33, v160
	s_add_i32 s26, s26, s34
	ds_read_b128 v[198:201], v206
	ds_read_b128 v[202:205], v206 offset:1024
	ds_read_b128 v[226:229], v206 offset:2048
	ds_read_b128 v[230:233], v206 offset:3072
	v_lshl_add_u64 v[206:207], s[10:11], 0, v[0:1]
	s_mov_b32 m0, s26
	v_lshl_add_u64 v[234:235], s[10:11], 0, v[138:139]
	global_load_lds_dwordx4 v[206:207], off
	s_add_i32 m0, s26, 0x2000
	s_nop 0
	global_load_lds_dwordx4 v[234:235], off
	s_barrier
	s_waitcnt lgkmcnt(0)
	s_waitcnt lgkmcnt(0)
	v_mfma_f32_16x16x32_bf16 v[118:121], v[198:201], v[166:169], v[118:121]
	v_mfma_f32_16x16x32_bf16 v[114:117], v[226:229], v[166:169], v[114:117]
	v_mfma_f32_16x16x32_bf16 v[102:105], v[198:201], v[174:177], v[102:105]
	v_mfma_f32_16x16x32_bf16 v[98:101], v[226:229], v[174:177], v[98:101]
	v_mfma_f32_16x16x32_bf16 v[86:89], v[198:201], v[182:185], v[86:89]
	v_mfma_f32_16x16x32_bf16 v[82:85], v[226:229], v[182:185], v[82:85]
	v_mfma_f32_16x16x32_bf16 v[70:73], v[198:201], v[190:193], v[70:73]
	v_mfma_f32_16x16x32_bf16 v[66:69], v[226:229], v[190:193], v[66:69]
	v_mfma_f32_16x16x32_bf16 v[118:121], v[202:205], v[170:173], v[118:121]
	v_mfma_f32_16x16x32_bf16 v[114:117], v[230:233], v[170:173], v[114:117]
	v_mfma_f32_16x16x32_bf16 v[102:105], v[202:205], v[178:181], v[102:105]
	v_mfma_f32_16x16x32_bf16 v[98:101], v[230:233], v[178:181], v[98:101]
	v_mfma_f32_16x16x32_bf16 v[86:89], v[202:205], v[186:189], v[86:89]
	v_mfma_f32_16x16x32_bf16 v[82:85], v[230:233], v[186:189], v[82:85]
	v_mfma_f32_16x16x32_bf16 v[70:73], v[202:205], v[194:197], v[70:73]
	v_mfma_f32_16x16x32_bf16 v[66:69], v[230:233], v[194:197], v[66:69]
	s_mov_b32 m0, s35
	v_lshl_add_u64 v[236:237], s[18:19], 0, v[148:149]
	s_barrier
	ds_read_b128 v[166:169], v161 offset:16384
	ds_read_b128 v[170:173], v161 offset:17408
	ds_read_b128 v[174:177], v161 offset:18432
	ds_read_b128 v[178:181], v161 offset:19456
	ds_read_b128 v[182:185], v161 offset:20480
	ds_read_b128 v[186:189], v161 offset:21504
	ds_read_b128 v[190:193], v161 offset:22528
	ds_read_b128 v[194:197], v161 offset:23552
	global_load_lds_dwordx4 v[236:237], off
	v_lshl_add_u64 v[238:239], s[18:19], 0, v[140:141]
	s_mov_b32 m0, s75
	s_nop 0
	global_load_lds_dwordx4 v[238:239], off
	s_barrier
	s_waitcnt lgkmcnt(0)
	s_waitcnt lgkmcnt(0)
	v_mfma_f32_16x16x32_bf16 v[62:65], v[130:133], v[166:169], v[62:65]
	v_mfma_f32_16x16x32_bf16 v[58:61], v[156:159], v[166:169], v[58:61]
	v_mfma_f32_16x16x32_bf16 v[46:49], v[130:133], v[174:177], v[46:49]
	v_mfma_f32_16x16x32_bf16 v[42:45], v[156:159], v[174:177], v[42:45]
	v_mfma_f32_16x16x32_bf16 v[30:33], v[130:133], v[182:185], v[30:33]
	v_mfma_f32_16x16x32_bf16 v[26:29], v[156:159], v[182:185], v[26:29]
	v_mfma_f32_16x16x32_bf16 v[14:17], v[130:133], v[190:193], v[14:17]
	v_mfma_f32_16x16x32_bf16 v[10:13], v[156:159], v[190:193], v[10:13]
	v_mfma_f32_16x16x32_bf16 v[62:65], v[134:137], v[170:173], v[62:65]
	v_mfma_f32_16x16x32_bf16 v[58:61], v[162:165], v[170:173], v[58:61]
	v_mfma_f32_16x16x32_bf16 v[46:49], v[134:137], v[178:181], v[46:49]
	v_mfma_f32_16x16x32_bf16 v[42:45], v[162:165], v[178:181], v[42:45]
	v_mfma_f32_16x16x32_bf16 v[30:33], v[134:137], v[186:189], v[30:33]
	v_mfma_f32_16x16x32_bf16 v[26:29], v[162:165], v[186:189], v[26:29]
	v_mfma_f32_16x16x32_bf16 v[14:17], v[134:137], v[194:197], v[14:17]
	v_mfma_f32_16x16x32_bf16 v[10:13], v[162:165], v[194:197], v[10:13]
	s_barrier
; #define PG8_STAGE(bufoff, gbase, voff) do { _Pragma("unroll") for (int _i = 0; _i < 2; ++_i) \
;     __builtin_amdgcn_global_load_lds((const unsigned*)((const char*)(gbase) + (voff)[_i]), (PG8_LAS unsigned*)(lds + (bufoff) + ldsw + _i * 8192), 16, 0, 0); } while (0)
; #define PG8_LDA(dst, b, h) do { _Pragma("unroll") for (int m = 0; m < 4; ++m) _Pragma("unroll") for (int k = 0; k < 2; ++k) dst[m][k] = *(const PG8_LAS bf16x8*)(lds + PG8_SA(b, h) + aoff + m * 2048 + k * 1024); } while (0)
; #define PG8_LDB(dst, b, h) do { _Pragma("unroll") for (int n = 0; n < 2; ++n) _Pragma("unroll") for (int k = 0; k < 2; ++k) dst[n][k] = *(const PG8_LAS bf16x8*)(lds + PG8_SB(b, h) + boff + n * 2048 + k * 1024); } while (0)
; #define PG8_WAIT_V(n) asm volatile("s_waitcnt vmcnt(" #n ")" ::: "memory")
; template <class Epi>
; DI void gemm_phase(PG8_LAS unsigned char* lds, const Gemm g, const StaticOrder& S, const Epi& E) {
;     ...
;     for (int t = 0; t < nt; t += 2) {
;       const bool last = (t == nt - 2);
;       const char* a1 = cA + (size_t)(t + 1) * kstep;
;       const char* a2 = last ? nA : cA + (size_t)(t + 2) * kstep; const char* b2 = last ? nB : cB + (size_t)(t + 2) * kstep;
;       const char* a3 = a2 + kstep; const char* b3 = b2 + kstep;
;       PG8_LDB(B0, 0, 0); PG8_SCHED; PG8_LDA(At, 0, 0); PG8_STAGE(PG8_SA(1, 1), a1 + hstepA, voffA);
;       PG8_WAIT_L(8); PG8_BAR; PG8_WAIT_L(0); PG8_MMA(0, 0, At, B0); PG8_BAR; PG8_SCHED;
;       PG8_LDB(B1, 0, 1); PG8_STAGE(PG8_SB(0, 0), b2, voffB);
;       PG8_BAR; PG8_WAIT_L(0); PG8_MMA(0, 1, At, B1); PG8_BAR;
;       PG8_LDA(At, 0, 1); PG8_STAGE(PG8_SA(0, 0), a2, voffA);
;       PG8_BAR; PG8_WAIT_L(0); PG8_MMA(1, 0, At, B0); PG8_BAR; PG8_SCHED;
;       PG8_STAGE(PG8_SB(0, 1), b2 + hstepB, voffB);
;       PG8_WAIT_V(6); PG8_BAR; PG8_MMA(1, 1, At, B1); PG8_BAR;
;       PG8_LDB(B0, 1, 0); PG8_SCHED; PG8_LDA(At, 1, 0); PG8_STAGE(PG8_SA(0, 1), a2 + hstepA, voffA);
;       PG8_WAIT_L(8); PG8_BAR; PG8_WAIT_L(0); PG8_MMA(0, 0, At, B0); PG8_BAR; PG8_SCHED;
;       PG8_LDB(B1, 1, 1); PG8_STAGE(PG8_SB(1, 0), b3, voffB);
;       PG8_BAR; PG8_WAIT_L(0); PG8_MMA(0, 1, At, B1); PG8_BAR;
;       PG8_LDA(At, 1, 1); PG8_STAGE(PG8_SA(1, 0), a3, voffA);
;       PG8_BAR; PG8_WAIT_L(0); PG8_MMA(1, 0, At, B0); PG8_BAR; PG8_SCHED;
;       PG8_STAGE(PG8_SB(1, 1), b3 + hstepB, voffB);
;       PG8_WAIT_V(6); PG8_BAR; PG8_MMA(1, 1, At, B1); PG8_BAR;
	s_add_u32 s26, s10, 0x40000
	s_addc_u32 s27, s11, 0
	s_add_i32 s33, s33, s34
	v_lshl_add_u64 v[130:131], s[26:27], 0, v[0:1]
	s_mov_b32 m0, s33
	s_nop 0
	global_load_lds_dwordx4 v[130:131], off
	v_lshl_add_u64 v[130:131], s[26:27], 0, v[138:139]
	s_add_i32 m0, s33, 0x2000
	s_nop 0
	global_load_lds_dwordx4 v[130:131], off
	s_waitcnt vmcnt(6)
	s_barrier
	v_mfma_f32_16x16x32_bf16 v[54:57], v[198:201], v[166:169], v[54:57]
	v_mfma_f32_16x16x32_bf16 v[50:53], v[226:229], v[166:169], v[50:53]
	v_mfma_f32_16x16x32_bf16 v[38:41], v[198:201], v[174:177], v[38:41]
	v_mfma_f32_16x16x32_bf16 v[34:37], v[226:229], v[174:177], v[34:37]
	v_mfma_f32_16x16x32_bf16 v[22:25], v[198:201], v[182:185], v[22:25]
	v_mfma_f32_16x16x32_bf16 v[18:21], v[226:229], v[182:185], v[18:21]
	v_mfma_f32_16x16x32_bf16 v[6:9], v[198:201], v[190:193], v[6:9]
	v_mfma_f32_16x16x32_bf16 v[2:5], v[226:229], v[190:193], v[2:5]
	v_mfma_f32_16x16x32_bf16 v[54:57], v[202:205], v[170:173], v[54:57]
	v_mfma_f32_16x16x32_bf16 v[50:53], v[230:233], v[170:173], v[50:53]
	v_mfma_f32_16x16x32_bf16 v[38:41], v[202:205], v[178:181], v[38:41]
	v_mfma_f32_16x16x32_bf16 v[34:37], v[230:233], v[178:181], v[34:37]
	v_mfma_f32_16x16x32_bf16 v[22:25], v[202:205], v[186:189], v[22:25]
	v_mfma_f32_16x16x32_bf16 v[18:21], v[230:233], v[186:189], v[18:21]
	v_mfma_f32_16x16x32_bf16 v[6:9], v[202:205], v[194:197], v[6:9]
	v_mfma_f32_16x16x32_bf16 v[2:5], v[230:233], v[194:197], v[2:5]
	s_add_i32 s26, 0, 0x18000
	v_add_u32_e32 v162, s26, v160
	s_barrier
	ds_read_b128 v[130:133], v162
	ds_read_b128 v[134:137], v162 offset:1024
	ds_read_b128 v[156:159], v162 offset:2048
	ds_read_b128 v[162:165], v162 offset:3072
	s_add_u32 s18, s18, 0x40000
	s_addc_u32 s19, s19, 0
	s_mov_b32 m0, s84
	v_lshl_add_u64 v[198:199], s[18:19], 0, v[148:149]
	ds_read_b128 v[166:169], v161 offset:32768
	ds_read_b128 v[170:173], v161 offset:33792
	ds_read_b128 v[174:177], v161 offset:34816
	ds_read_b128 v[178:181], v161 offset:35840
	ds_read_b128 v[182:185], v161 offset:36864
	ds_read_b128 v[186:189], v161 offset:37888
	ds_read_b128 v[190:193], v161 offset:38912
	ds_read_b128 v[194:197], v161 offset:39936
	global_load_lds_dwordx4 v[198:199], off
	v_lshl_add_u64 v[198:199], s[18:19], 0, v[140:141]
	s_mov_b32 m0, s85
	s_nop 0
	global_load_lds_dwordx4 v[198:199], off
	s_waitcnt lgkmcnt(8)
	s_barrier
	s_waitcnt lgkmcnt(0)
	s_waitcnt lgkmcnt(0)
	v_mfma_f32_16x16x32_bf16 v[126:129], v[130:133], v[166:169], v[126:129]
	v_mfma_f32_16x16x32_bf16 v[122:125], v[156:159], v[166:169], v[122:125]
	v_mfma_f32_16x16x32_bf16 v[110:113], v[130:133], v[174:177], v[110:113]
	v_mfma_f32_16x16x32_bf16 v[106:109], v[156:159], v[174:177], v[106:109]
	v_mfma_f32_16x16x32_bf16 v[94:97], v[130:133], v[182:185], v[94:97]
	v_mfma_f32_16x16x32_bf16 v[90:93], v[156:159], v[182:185], v[90:93]
	v_mfma_f32_16x16x32_bf16 v[78:81], v[130:133], v[190:193], v[78:81]
	v_mfma_f32_16x16x32_bf16 v[74:77], v[156:159], v[190:193], v[74:77]
	v_mfma_f32_16x16x32_bf16 v[126:129], v[134:137], v[170:173], v[126:129]
	v_mfma_f32_16x16x32_bf16 v[122:125], v[162:165], v[170:173], v[122:125]
	v_mfma_f32_16x16x32_bf16 v[110:113], v[134:137], v[178:181], v[110:113]
	v_mfma_f32_16x16x32_bf16 v[106:109], v[162:165], v[178:181], v[106:109]
	v_mfma_f32_16x16x32_bf16 v[94:97], v[134:137], v[186:189], v[94:97]
	v_mfma_f32_16x16x32_bf16 v[90:93], v[162:165], v[186:189], v[90:93]
	v_mfma_f32_16x16x32_bf16 v[78:81], v[134:137], v[194:197], v[78:81]
	v_mfma_f32_16x16x32_bf16 v[74:77], v[162:165], v[194:197], v[74:77]
	s_barrier
	s_add_i32 s18, 0, 0x1c000
	s_add_i32 s19, s26, s34
	v_add_u32_e32 v212, s18, v160
	v_lshl_add_u64 v[206:207], v[206:207], 0, s[82:83]
	s_mov_b32 m0, s19
	ds_read_b128 v[198:201], v212
	ds_read_b128 v[202:205], v212 offset:1024
	ds_read_b128 v[226:229], v212 offset:2048
	ds_read_b128 v[230:233], v212 offset:3072
	global_load_lds_dwordx4 v[206:207], off
	v_lshl_add_u64 v[206:207], v[234:235], 0, s[82:83]
	s_add_i32 m0, s19, 0x2000
	s_nop 0
	global_load_lds_dwordx4 v[206:207], off
	s_barrier
; DI float silu_f(float x) { return x * __builtin_amdgcn_rcpf(1.f + __expf(-x)); }
; #define PG8_STAGE(bufoff, gbase, voff) do { _Pragma("unroll") for (int _i = 0; _i < 2; ++_i) \
;     __builtin_amdgcn_global_load_lds((const unsigned*)((const char*)(gbase) + (voff)[_i]), (PG8_LAS unsigned*)(lds + (bufoff) + ldsw + _i * 8192), 16, 0, 0); } while (0)
; #define PG8_LDA(dst, b, h) do { _Pragma("unroll") for (int m = 0; m < 4; ++m) _Pragma("unroll") for (int k = 0; k < 2; ++k) dst[m][k] = *(const PG8_LAS bf16x8*)(lds + PG8_SA(b, h) + aoff + m * 2048 + k * 1024); } while (0)
; #define PG8_WAIT_V(n) asm volatile("s_waitcnt vmcnt(" #n ")" ::: "memory")
; #define PG8_BAR __builtin_amdgcn_s_barrier()
; template <class Epi>
; DI void gemm_phase(PG8_LAS unsigned char* lds, const Gemm g, const StaticOrder& S, const Epi& E) {
;     ...
;       PG8_LDB(B0, 0, 0); PG8_SCHED; PG8_LDA(At, 0, 0); PG8_STAGE(PG8_SA(1, 1), a1 + hstepA, voffA);
;       PG8_WAIT_L(8); PG8_BAR; PG8_WAIT_L(0); PG8_MMA(0, 0, At, B0); PG8_BAR; PG8_SCHED;
;       PG8_LDB(B1, 0, 1); PG8_STAGE(PG8_SB(0, 0), b2, voffB);
;       PG8_BAR; PG8_WAIT_L(0); PG8_MMA(0, 1, At, B1); PG8_BAR;
;       PG8_LDA(At, 0, 1); PG8_STAGE(PG8_SA(0, 0), a2, voffA);
;       PG8_BAR; PG8_WAIT_L(0); PG8_MMA(1, 0, At, B0); PG8_BAR; PG8_SCHED;
;       PG8_STAGE(PG8_SB(0, 1), b2 + hstepB, voffB);
;       PG8_WAIT_V(6); PG8_BAR; PG8_MMA(1, 1, At, B1); PG8_BAR;
;       PG8_LDB(B0, 1, 0); PG8_SCHED; PG8_LDA(At, 1, 0); PG8_STAGE(PG8_SA(0, 1), a2 + hstepA, voffA);
;       PG8_WAIT_L(8); PG8_BAR; PG8_WAIT_L(0); PG8_MMA(0, 0, At, B0); PG8_BAR; PG8_SCHED;
;       PG8_LDB(B1, 1, 1); PG8_STAGE(PG8_SB(1, 0), b3, voffB);
;       PG8_BAR; PG8_WAIT_L(0); PG8_MMA(0, 1, At, B1); PG8_BAR;
;       PG8_LDA(At, 1, 1); PG8_STAGE(PG8_SA(1, 0), a3, voffA);
;       PG8_BAR; PG8_WAIT_L(0); PG8_MMA(1, 0, At, B0); PG8_BAR; PG8_SCHED;
;       PG8_STAGE(PG8_SB(1, 1), b3 + hstepB, voffB);
;       PG8_WAIT_V(6); PG8_BAR; PG8_MMA(1, 1, At, B1); PG8_BAR;
;   DI void operator()(const f32x4 (&acc)[2][2][4][2], const pg8::Unit& un, int wr, int wc, int fr, int fq) const {
;     ...
;             if (c128 >= vend) {
; #pragma unroll
;               for (int e = 0; e < 4; ++e) { v0[e] = silu_f(v0[e]); v1[e] = silu_f(v1[e]); }
;             } else if (c128 < 1024) {
;               v0 = v0 * (0.125f * 1.4426950408889634f); v1 = v1 * (0.125f * 1.4426950408889634f);
;             }
	s_waitcnt lgkmcnt(0)
	s_waitcnt lgkmcnt(0)
	v_mfma_f32_16x16x32_bf16 v[118:121], v[198:201], v[166:169], v[118:121]
	v_mfma_f32_16x16x32_bf16 v[114:117], v[226:229], v[166:169], v[114:117]
	v_mfma_f32_16x16x32_bf16 v[102:105], v[198:201], v[174:177], v[102:105]
	v_mfma_f32_16x16x32_bf16 v[98:101], v[226:229], v[174:177], v[98:101]
	v_mfma_f32_16x16x32_bf16 v[86:89], v[198:201], v[182:185], v[86:89]
	v_mfma_f32_16x16x32_bf16 v[82:85], v[226:229], v[182:185], v[82:85]
	v_mfma_f32_16x16x32_bf16 v[70:73], v[198:201], v[190:193], v[70:73]
	v_mfma_f32_16x16x32_bf16 v[66:69], v[226:229], v[190:193], v[66:69]
	v_mfma_f32_16x16x32_bf16 v[118:121], v[202:205], v[170:173], v[118:121]
	v_mfma_f32_16x16x32_bf16 v[114:117], v[230:233], v[170:173], v[114:117]
	v_mfma_f32_16x16x32_bf16 v[102:105], v[202:205], v[178:181], v[102:105]
	v_mfma_f32_16x16x32_bf16 v[98:101], v[230:233], v[178:181], v[98:101]
	v_mfma_f32_16x16x32_bf16 v[86:89], v[202:205], v[186:189], v[86:89]
	v_mfma_f32_16x16x32_bf16 v[82:85], v[230:233], v[186:189], v[82:85]
	v_mfma_f32_16x16x32_bf16 v[70:73], v[202:205], v[194:197], v[70:73]
	v_mfma_f32_16x16x32_bf16 v[66:69], v[230:233], v[194:197], v[66:69]
	s_mov_b32 m0, s86
	v_lshl_add_u64 v[206:207], v[236:237], 0, s[82:83]
	s_barrier
	ds_read_b128 v[166:169], v161 offset:49152
	ds_read_b128 v[170:173], v161 offset:50176
	ds_read_b128 v[174:177], v161 offset:51200
	ds_read_b128 v[178:181], v161 offset:52224
	ds_read_b128 v[182:185], v161 offset:53248
	ds_read_b128 v[186:189], v161 offset:54272
	ds_read_b128 v[190:193], v161 offset:55296
	ds_read_b128 v[194:197], v161 offset:56320
	global_load_lds_dwordx4 v[206:207], off
	v_lshl_add_u64 v[206:207], v[238:239], 0, s[82:83]
	s_mov_b32 m0, s87
	s_nop 0
	global_load_lds_dwordx4 v[206:207], off
	s_barrier
	s_waitcnt lgkmcnt(0)
	s_waitcnt lgkmcnt(0)
	v_mfma_f32_16x16x32_bf16 v[62:65], v[130:133], v[166:169], v[62:65]
	v_mfma_f32_16x16x32_bf16 v[58:61], v[156:159], v[166:169], v[58:61]
	v_mfma_f32_16x16x32_bf16 v[46:49], v[130:133], v[174:177], v[46:49]
	v_mfma_f32_16x16x32_bf16 v[42:45], v[156:159], v[174:177], v[42:45]
	v_mfma_f32_16x16x32_bf16 v[30:33], v[130:133], v[182:185], v[30:33]
	v_mfma_f32_16x16x32_bf16 v[26:29], v[156:159], v[182:185], v[26:29]
	v_mfma_f32_16x16x32_bf16 v[14:17], v[130:133], v[190:193], v[14:17]
	v_mfma_f32_16x16x32_bf16 v[10:13], v[156:159], v[190:193], v[10:13]
	v_mfma_f32_16x16x32_bf16 v[62:65], v[134:137], v[170:173], v[62:65]
	v_mfma_f32_16x16x32_bf16 v[58:61], v[162:165], v[170:173], v[58:61]
	v_mfma_f32_16x16x32_bf16 v[46:49], v[134:137], v[178:181], v[46:49]
	v_mfma_f32_16x16x32_bf16 v[42:45], v[162:165], v[178:181], v[42:45]
	v_mfma_f32_16x16x32_bf16 v[30:33], v[134:137], v[186:189], v[30:33]
	v_mfma_f32_16x16x32_bf16 v[26:29], v[162:165], v[186:189], v[26:29]
	v_mfma_f32_16x16x32_bf16 v[14:17], v[134:137], v[194:197], v[14:17]
	v_mfma_f32_16x16x32_bf16 v[10:13], v[162:165], v[194:197], v[10:13]
	s_barrier
	s_add_u32 s10, s10, 0x40080
	s_addc_u32 s11, s11, 0
	s_add_i32 s18, s18, s34
	v_lshl_add_u64 v[130:131], s[10:11], 0, v[0:1]
	s_mov_b32 m0, s18
	s_nop 0
	global_load_lds_dwordx4 v[130:131], off
	v_lshl_add_u64 v[130:131], s[10:11], 0, v[138:139]
	s_add_i32 m0, s18, 0x2000
	s_nop 0
	global_load_lds_dwordx4 v[130:131], off
	s_waitcnt vmcnt(6)
	s_barrier
	v_mfma_f32_16x16x32_bf16 v[54:57], v[198:201], v[166:169], v[54:57]
	v_mfma_f32_16x16x32_bf16 v[50:53], v[226:229], v[166:169], v[50:53]
	v_mfma_f32_16x16x32_bf16 v[38:41], v[198:201], v[174:177], v[38:41]
	v_mfma_f32_16x16x32_bf16 v[34:37], v[226:229], v[174:177], v[34:37]
	v_mfma_f32_16x16x32_bf16 v[22:25], v[198:201], v[182:185], v[22:25]
	v_mfma_f32_16x16x32_bf16 v[18:21], v[226:229], v[182:185], v[18:21]
	v_mfma_f32_16x16x32_bf16 v[6:9], v[198:201], v[190:193], v[6:9]
	v_mfma_f32_16x16x32_bf16 v[2:5], v[226:229], v[190:193], v[2:5]
	v_mfma_f32_16x16x32_bf16 v[54:57], v[202:205], v[170:173], v[54:57]
	v_mfma_f32_16x16x32_bf16 v[50:53], v[230:233], v[170:173], v[50:53]
	v_mfma_f32_16x16x32_bf16 v[38:41], v[202:205], v[178:181], v[38:41]
	v_mfma_f32_16x16x32_bf16 v[34:37], v[230:233], v[178:181], v[34:37]
	v_mfma_f32_16x16x32_bf16 v[22:25], v[202:205], v[186:189], v[22:25]
	v_mfma_f32_16x16x32_bf16 v[18:21], v[230:233], v[186:189], v[18:21]
	v_mfma_f32_16x16x32_bf16 v[6:9], v[202:205], v[194:197], v[6:9]
	v_mfma_f32_16x16x32_bf16 v[2:5], v[230:233], v[194:197], v[2:5]
	s_add_i32 s25, s25, 2
	s_add_u32 s8, s8, 0x100
	s_addc_u32 s9, s9, 0
	s_add_u32 s23, s23, 0x100
	s_addc_u32 s24, s24, 0
	s_cmp_gt_u32 s25, 13
	s_barrier
	s_cbranch_scc0 .LBB0_220
	s_cmp_lt_i32 s89, 12
	s_cselect_b64 s[10:11], -1, 0
	s_mov_b64 s[8:9], -1
	s_and_b64 vcc, exec, s[10:11]
	s_cbranch_vccz .LBB0_225
	v_mov_b64_e32 v[136:137], v[124:125]
	v_mov_b64_e32 v[132:133], v[128:129]
	s_cmp_gt_i32 s89, 3
	v_mov_b64_e32 v[134:135], v[122:123]
	v_mov_b64_e32 v[130:131], v[126:127]
	s_cbranch_scc1 .LBB0_224
	v_pk_mul_f32 v[132:133], v[128:129], s[94:95] op_sel_hi:[1,0]
	v_pk_mul_f32 v[130:131], v[126:127], s[94:95] op_sel_hi:[1,0]
	v_pk_mul_f32 v[136:137], v[124:125], s[94:95] op_sel_hi:[1,0]
	v_pk_mul_f32 v[134:135], v[122:123], s[94:95] op_sel_hi:[1,0]

; #define PG8_STAGE(bufoff, gbase, voff) do { _Pragma("unroll") for (int _i = 0; _i < 2; ++_i) \
;     __builtin_amdgcn_global_load_lds((const unsigned*)((const char*)(gbase) + (voff)[_i]), (PG8_LAS unsigned*)(lds + (bufoff) + ldsw + _i * 8192), 16, 0, 0); } while (0)
; #define PG8_LDA(dst, b, h) do { _Pragma("unroll") for (int m = 0; m < 4; ++m) _Pragma("unroll") for (int k = 0; k < 2; ++k) dst[m][k] = *(const PG8_LAS bf16x8*)(lds + PG8_SA(b, h) + aoff + m * 2048 + k * 1024); } while (0)
; #define PG8_LDB(dst, b, h) do { _Pragma("unroll") for (int n = 0; n < 2; ++n) _Pragma("unroll") for (int k = 0; k < 2; ++k) dst[n][k] = *(const PG8_LAS bf16x8*)(lds + PG8_SB(b, h) + boff + n * 2048 + k * 1024); } while (0)
; #define PG8_WAIT_V(n) asm volatile("s_waitcnt vmcnt(" #n ")" ::: "memory")
; template <class Epi>
; DI void gemm_phase(PG8_LAS unsigned char* lds, const Gemm g, const StaticOrder& S, const Epi& E) {
;     ...
;     for (int t = 0; t < nt; t += 2) {
;       const bool last = (t == nt - 2);
;       const char* a1 = cA + (size_t)(t + 1) * kstep;
;       const char* a2 = last ? nA : cA + (size_t)(t + 2) * kstep; const char* b2 = last ? nB : cB + (size_t)(t + 2) * kstep;
;       const char* a3 = a2 + kstep; const char* b3 = b2 + kstep;
;       PG8_LDB(B0, 0, 0); PG8_SCHED; PG8_LDA(At, 0, 0); PG8_STAGE(PG8_SA(1, 1), a1 + hstepA, voffA);
;       PG8_WAIT_L(8); PG8_BAR; PG8_WAIT_L(0); PG8_MMA(0, 0, At, B0); PG8_BAR; PG8_SCHED;
;       PG8_LDB(B1, 0, 1); PG8_STAGE(PG8_SB(0, 0), b2, voffB);
;       PG8_BAR; PG8_WAIT_L(0); PG8_MMA(0, 1, At, B1); PG8_BAR;
;       PG8_LDA(At, 0, 1); PG8_STAGE(PG8_SA(0, 0), a2, voffA);
;       PG8_BAR; PG8_WAIT_L(0); PG8_MMA(1, 0, At, B0); PG8_BAR; PG8_SCHED;
;       PG8_STAGE(PG8_SB(0, 1), b2 + hstepB, voffB);
;       PG8_WAIT_V(6); PG8_BAR; PG8_MMA(1, 1, At, B1); PG8_BAR;
;       PG8_LDB(B0, 1, 0); PG8_SCHED; PG8_LDA(At, 1, 0); PG8_STAGE(PG8_SA(0, 1), a2 + hstepA, voffA);
;       PG8_WAIT_L(8); PG8_BAR; PG8_WAIT_L(0); PG8_MMA(0, 0, At, B0); PG8_BAR; PG8_SCHED;
;       PG8_LDB(B1, 1, 1); PG8_STAGE(PG8_SB(1, 0), b3, voffB);
;       PG8_BAR; PG8_WAIT_L(0); PG8_MMA(0, 1, At, B1); PG8_BAR;
;       PG8_LDA(At, 1, 1); PG8_STAGE(PG8_SA(1, 0), a3, voffA);
;       PG8_BAR; PG8_WAIT_L(0); PG8_MMA(1, 0, At, B0); PG8_BAR; PG8_SCHED;
;       PG8_STAGE(PG8_SB(1, 1), b3 + hstepB, voffB);
;       PG8_WAIT_V(6); PG8_BAR; PG8_MMA(1, 1, At, B1); PG8_BAR;
.LBB0_351:
	s_add_u32 s10, s8, 0xfffc0080
	s_addc_u32 s11, s9, -1
	s_add_i32 s26, 0, 0x10000
	v_add_u32_e32 v162, s26, v142
	ds_read_b128 v[130:133], v162
	ds_read_b128 v[134:137], v162 offset:1024
	ds_read_b128 v[156:159], v162 offset:2048
	ds_read_b128 v[162:165], v162 offset:3072
	s_cmp_eq_u32 s25, 12
	s_cselect_b32 s19, s13, s11
	s_cselect_b32 s18, s21, s10
	s_cselect_b32 s11, s1, s24
	s_cselect_b32 s10, s22, s23
	v_lshl_add_u64 v[198:199], s[8:9], 0, v[152:153]
	s_add_i32 m0, s84, 0xc000
	ds_read_b128 v[166:169], v161
	ds_read_b128 v[170:173], v161 offset:1024
	ds_read_b128 v[174:177], v161 offset:2048
	ds_read_b128 v[178:181], v161 offset:3072
	ds_read_b128 v[182:185], v161 offset:4096
	ds_read_b128 v[186:189], v161 offset:5120
	ds_read_b128 v[190:193], v161 offset:6144
	ds_read_b128 v[194:197], v161 offset:7168
	global_load_lds_dwordx4 v[198:199], off
	v_lshl_add_u64 v[198:199], s[8:9], 0, v[154:155]
	s_add_i32 m0, s84, 0xe000
	s_nop 0
	global_load_lds_dwordx4 v[198:199], off
	s_waitcnt lgkmcnt(8)
	s_barrier
	s_waitcnt lgkmcnt(0)
	s_waitcnt lgkmcnt(0)
	v_mfma_f32_16x16x32_bf16 v[126:129], v[130:133], v[166:169], v[126:129]
	v_mfma_f32_16x16x32_bf16 v[122:125], v[156:159], v[166:169], v[122:125]
	v_mfma_f32_16x16x32_bf16 v[110:113], v[130:133], v[174:177], v[110:113]
	v_mfma_f32_16x16x32_bf16 v[106:109], v[156:159], v[174:177], v[106:109]
	v_mfma_f32_16x16x32_bf16 v[94:97], v[130:133], v[182:185], v[94:97]
	v_mfma_f32_16x16x32_bf16 v[90:93], v[156:159], v[182:185], v[90:93]
	v_mfma_f32_16x16x32_bf16 v[78:81], v[130:133], v[190:193], v[78:81]
	v_mfma_f32_16x16x32_bf16 v[74:77], v[156:159], v[190:193], v[74:77]
	v_mfma_f32_16x16x32_bf16 v[126:129], v[134:137], v[170:173], v[126:129]
	v_mfma_f32_16x16x32_bf16 v[122:125], v[162:165], v[170:173], v[122:125]
	v_mfma_f32_16x16x32_bf16 v[110:113], v[134:137], v[178:181], v[110:113]
	v_mfma_f32_16x16x32_bf16 v[106:109], v[162:165], v[178:181], v[106:109]
	v_mfma_f32_16x16x32_bf16 v[94:97], v[134:137], v[186:189], v[94:97]
	v_mfma_f32_16x16x32_bf16 v[90:93], v[162:165], v[186:189], v[90:93]
	v_mfma_f32_16x16x32_bf16 v[78:81], v[134:137], v[194:197], v[78:81]
	v_mfma_f32_16x16x32_bf16 v[74:77], v[162:165], v[194:197], v[74:77]
	s_barrier
	s_add_i32 s33, 0, 0x14000
	v_add_u32_e32 v206, s33, v142
	s_add_i32 s26, s26, s75
	ds_read_b128 v[198:201], v206
	ds_read_b128 v[202:205], v206 offset:1024
	ds_read_b128 v[226:229], v206 offset:2048
	ds_read_b128 v[230:233], v206 offset:3072
	v_lshl_add_u64 v[206:207], s[10:11], 0, v[0:1]
	s_mov_b32 m0, s26
	v_lshl_add_u64 v[234:235], s[10:11], 0, v[138:139]
	global_load_lds_dwordx4 v[206:207], off
	s_add_i32 m0, s26, 0x2000
	s_nop 0
	global_load_lds_dwordx4 v[234:235], off
	s_barrier
	s_waitcnt lgkmcnt(0)
	s_waitcnt lgkmcnt(0)
	v_mfma_f32_16x16x32_bf16 v[118:121], v[198:201], v[166:169], v[118:121]
	v_mfma_f32_16x16x32_bf16 v[114:117], v[226:229], v[166:169], v[114:117]
	v_mfma_f32_16x16x32_bf16 v[102:105], v[198:201], v[174:177], v[102:105]
	v_mfma_f32_16x16x32_bf16 v[98:101], v[226:229], v[174:177], v[98:101]
	v_mfma_f32_16x16x32_bf16 v[86:89], v[198:201], v[182:185], v[86:89]
	v_mfma_f32_16x16x32_bf16 v[82:85], v[226:229], v[182:185], v[82:85]
	v_mfma_f32_16x16x32_bf16 v[70:73], v[198:201], v[190:193], v[70:73]
	v_mfma_f32_16x16x32_bf16 v[66:69], v[226:229], v[190:193], v[66:69]
	v_mfma_f32_16x16x32_bf16 v[118:121], v[202:205], v[170:173], v[118:121]
	v_mfma_f32_16x16x32_bf16 v[114:117], v[230:233], v[170:173], v[114:117]
	v_mfma_f32_16x16x32_bf16 v[102:105], v[202:205], v[178:181], v[102:105]
	v_mfma_f32_16x16x32_bf16 v[98:101], v[230:233], v[178:181], v[98:101]
	v_mfma_f32_16x16x32_bf16 v[86:89], v[202:205], v[186:189], v[86:89]
	v_mfma_f32_16x16x32_bf16 v[82:85], v[230:233], v[186:189], v[82:85]
	v_mfma_f32_16x16x32_bf16 v[70:73], v[202:205], v[194:197], v[70:73]
	v_mfma_f32_16x16x32_bf16 v[66:69], v[230:233], v[194:197], v[66:69]
	s_mov_b32 m0, s84
	v_lshl_add_u64 v[236:237], s[18:19], 0, v[148:149]
	s_barrier
	ds_read_b128 v[166:169], v161 offset:16384
	ds_read_b128 v[170:173], v161 offset:17408
	ds_read_b128 v[174:177], v161 offset:18432
	ds_read_b128 v[178:181], v161 offset:19456
	ds_read_b128 v[182:185], v161 offset:20480
	ds_read_b128 v[186:189], v161 offset:21504
	ds_read_b128 v[190:193], v161 offset:22528
	ds_read_b128 v[194:197], v161 offset:23552
	global_load_lds_dwordx4 v[236:237], off
	v_lshl_add_u64 v[238:239], s[18:19], 0, v[140:141]
	s_mov_b32 m0, s85
	s_nop 0
	global_load_lds_dwordx4 v[238:239], off
	s_barrier
	s_waitcnt lgkmcnt(0)
	s_waitcnt lgkmcnt(0)
	v_mfma_f32_16x16x32_bf16 v[62:65], v[130:133], v[166:169], v[62:65]
	v_mfma_f32_16x16x32_bf16 v[58:61], v[156:159], v[166:169], v[58:61]
	v_mfma_f32_16x16x32_bf16 v[46:49], v[130:133], v[174:177], v[46:49]
	v_mfma_f32_16x16x32_bf16 v[42:45], v[156:159], v[174:177], v[42:45]
	v_mfma_f32_16x16x32_bf16 v[30:33], v[130:133], v[182:185], v[30:33]
	v_mfma_f32_16x16x32_bf16 v[26:29], v[156:159], v[182:185], v[26:29]
	v_mfma_f32_16x16x32_bf16 v[14:17], v[130:133], v[190:193], v[14:17]
	v_mfma_f32_16x16x32_bf16 v[10:13], v[156:159], v[190:193], v[10:13]
	v_mfma_f32_16x16x32_bf16 v[62:65], v[134:137], v[170:173], v[62:65]
	v_mfma_f32_16x16x32_bf16 v[58:61], v[162:165], v[170:173], v[58:61]
	v_mfma_f32_16x16x32_bf16 v[46:49], v[134:137], v[178:181], v[46:49]
	v_mfma_f32_16x16x32_bf16 v[42:45], v[162:165], v[178:181], v[42:45]
	v_mfma_f32_16x16x32_bf16 v[30:33], v[134:137], v[186:189], v[30:33]
	v_mfma_f32_16x16x32_bf16 v[26:29], v[162:165], v[186:189], v[26:29]
	v_mfma_f32_16x16x32_bf16 v[14:17], v[134:137], v[194:197], v[14:17]
	v_mfma_f32_16x16x32_bf16 v[10:13], v[162:165], v[194:197], v[10:13]
	s_barrier
; #define PG8_STAGE(bufoff, gbase, voff) do { _Pragma("unroll") for (int _i = 0; _i < 2; ++_i) \
;     __builtin_amdgcn_global_load_lds((const unsigned*)((const char*)(gbase) + (voff)[_i]), (PG8_LAS unsigned*)(lds + (bufoff) + ldsw + _i * 8192), 16, 0, 0); } while (0)
; #define PG8_LDA(dst, b, h) do { _Pragma("unroll") for (int m = 0; m < 4; ++m) _Pragma("unroll") for (int k = 0; k < 2; ++k) dst[m][k] = *(const PG8_LAS bf16x8*)(lds + PG8_SA(b, h) + aoff + m * 2048 + k * 1024); } while (0)
; #define PG8_LDB(dst, b, h) do { _Pragma("unroll") for (int n = 0; n < 2; ++n) _Pragma("unroll") for (int k = 0; k < 2; ++k) dst[n][k] = *(const PG8_LAS bf16x8*)(lds + PG8_SB(b, h) + boff + n * 2048 + k * 1024); } while (0)
; #define PG8_WAIT_V(n) asm volatile("s_waitcnt vmcnt(" #n ")" ::: "memory")
; template <class Epi>
; DI void gemm_phase(PG8_LAS unsigned char* lds, const Gemm g, const StaticOrder& S, const Epi& E) {
;     ...
;     for (int t = 0; t < nt; t += 2) {
;       const bool last = (t == nt - 2);
;       const char* a1 = cA + (size_t)(t + 1) * kstep;
;       const char* a2 = last ? nA : cA + (size_t)(t + 2) * kstep; const char* b2 = last ? nB : cB + (size_t)(t + 2) * kstep;
;       const char* a3 = a2 + kstep; const char* b3 = b2 + kstep;
;       PG8_LDB(B0, 0, 0); PG8_SCHED; PG8_LDA(At, 0, 0); PG8_STAGE(PG8_SA(1, 1), a1 + hstepA, voffA);
;       PG8_WAIT_L(8); PG8_BAR; PG8_WAIT_L(0); PG8_MMA(0, 0, At, B0); PG8_BAR; PG8_SCHED;
;       PG8_LDB(B1, 0, 1); PG8_STAGE(PG8_SB(0, 0), b2, voffB);
;       PG8_BAR; PG8_WAIT_L(0); PG8_MMA(0, 1, At, B1); PG8_BAR;
;       PG8_LDA(At, 0, 1); PG8_STAGE(PG8_SA(0, 0), a2, voffA);
;       PG8_BAR; PG8_WAIT_L(0); PG8_MMA(1, 0, At, B0); PG8_BAR; PG8_SCHED;
;       PG8_STAGE(PG8_SB(0, 1), b2 + hstepB, voffB);
;       PG8_WAIT_V(6); PG8_BAR; PG8_MMA(1, 1, At, B1); PG8_BAR;
;       PG8_LDB(B0, 1, 0); PG8_SCHED; PG8_LDA(At, 1, 0); PG8_STAGE(PG8_SA(0, 1), a2 + hstepA, voffA);
;       PG8_WAIT_L(8); PG8_BAR; PG8_WAIT_L(0); PG8_MMA(0, 0, At, B0); PG8_BAR; PG8_SCHED;
;       PG8_LDB(B1, 1, 1); PG8_STAGE(PG8_SB(1, 0), b3, voffB);
;       PG8_BAR; PG8_WAIT_L(0); PG8_MMA(0, 1, At, B1); PG8_BAR;
;       PG8_LDA(At, 1, 1); PG8_STAGE(PG8_SA(1, 0), a3, voffA);
;       PG8_BAR; PG8_WAIT_L(0); PG8_MMA(1, 0, At, B0); PG8_BAR; PG8_SCHED;
;       PG8_STAGE(PG8_SB(1, 1), b3 + hstepB, voffB);
;       PG8_WAIT_V(6); PG8_BAR; PG8_MMA(1, 1, At, B1); PG8_BAR;
	s_add_u32 s26, s10, 0x40000
	s_addc_u32 s27, s11, 0
	s_add_i32 s33, s33, s75
	v_lshl_add_u64 v[130:131], s[26:27], 0, v[0:1]
	s_mov_b32 m0, s33
	s_nop 0
	global_load_lds_dwordx4 v[130:131], off
	v_lshl_add_u64 v[130:131], s[26:27], 0, v[138:139]
	s_add_i32 m0, s33, 0x2000
	s_nop 0
	global_load_lds_dwordx4 v[130:131], off
	s_waitcnt vmcnt(6)
	s_barrier
	v_mfma_f32_16x16x32_bf16 v[54:57], v[198:201], v[166:169], v[54:57]
	v_mfma_f32_16x16x32_bf16 v[50:53], v[226:229], v[166:169], v[50:53]
	v_mfma_f32_16x16x32_bf16 v[38:41], v[198:201], v[174:177], v[38:41]
	v_mfma_f32_16x16x32_bf16 v[34:37], v[226:229], v[174:177], v[34:37]
	v_mfma_f32_16x16x32_bf16 v[22:25], v[198:201], v[182:185], v[22:25]
	v_mfma_f32_16x16x32_bf16 v[18:21], v[226:229], v[182:185], v[18:21]
	v_mfma_f32_16x16x32_bf16 v[6:9], v[198:201], v[190:193], v[6:9]
	v_mfma_f32_16x16x32_bf16 v[2:5], v[226:229], v[190:193], v[2:5]
	v_mfma_f32_16x16x32_bf16 v[54:57], v[202:205], v[170:173], v[54:57]
	v_mfma_f32_16x16x32_bf16 v[50:53], v[230:233], v[170:173], v[50:53]
	v_mfma_f32_16x16x32_bf16 v[38:41], v[202:205], v[178:181], v[38:41]
	v_mfma_f32_16x16x32_bf16 v[34:37], v[230:233], v[178:181], v[34:37]
	v_mfma_f32_16x16x32_bf16 v[22:25], v[202:205], v[186:189], v[22:25]
	v_mfma_f32_16x16x32_bf16 v[18:21], v[230:233], v[186:189], v[18:21]
	v_mfma_f32_16x16x32_bf16 v[6:9], v[202:205], v[194:197], v[6:9]
	v_mfma_f32_16x16x32_bf16 v[2:5], v[230:233], v[194:197], v[2:5]
	s_add_i32 s26, 0, 0x18000
	v_add_u32_e32 v162, s26, v142
	s_barrier
	ds_read_b128 v[130:133], v162
	ds_read_b128 v[134:137], v162 offset:1024
	ds_read_b128 v[156:159], v162 offset:2048
	ds_read_b128 v[162:165], v162 offset:3072
	s_add_u32 s18, s18, 0x40000
	s_addc_u32 s19, s19, 0
	s_mov_b32 m0, s86
	v_lshl_add_u64 v[198:199], s[18:19], 0, v[148:149]
	ds_read_b128 v[166:169], v161 offset:32768
	ds_read_b128 v[170:173], v161 offset:33792
	ds_read_b128 v[174:177], v161 offset:34816
	ds_read_b128 v[178:181], v161 offset:35840
	ds_read_b128 v[182:185], v161 offset:36864
	ds_read_b128 v[186:189], v161 offset:37888
	ds_read_b128 v[190:193], v161 offset:38912
	ds_read_b128 v[194:197], v161 offset:39936
	global_load_lds_dwordx4 v[198:199], off
	v_lshl_add_u64 v[198:199], s[18:19], 0, v[140:141]
	s_mov_b32 m0, s87
	s_nop 0
	global_load_lds_dwordx4 v[198:199], off
	s_waitcnt lgkmcnt(8)
	s_barrier
	s_waitcnt lgkmcnt(0)
	s_waitcnt lgkmcnt(0)
	v_mfma_f32_16x16x32_bf16 v[126:129], v[130:133], v[166:169], v[126:129]
	v_mfma_f32_16x16x32_bf16 v[122:125], v[156:159], v[166:169], v[122:125]
	v_mfma_f32_16x16x32_bf16 v[110:113], v[130:133], v[174:177], v[110:113]
	v_mfma_f32_16x16x32_bf16 v[106:109], v[156:159], v[174:177], v[106:109]
	v_mfma_f32_16x16x32_bf16 v[94:97], v[130:133], v[182:185], v[94:97]
	v_mfma_f32_16x16x32_bf16 v[90:93], v[156:159], v[182:185], v[90:93]
	v_mfma_f32_16x16x32_bf16 v[78:81], v[130:133], v[190:193], v[78:81]
	v_mfma_f32_16x16x32_bf16 v[74:77], v[156:159], v[190:193], v[74:77]
	v_mfma_f32_16x16x32_bf16 v[126:129], v[134:137], v[170:173], v[126:129]
	v_mfma_f32_16x16x32_bf16 v[122:125], v[162:165], v[170:173], v[122:125]
	v_mfma_f32_16x16x32_bf16 v[110:113], v[134:137], v[178:181], v[110:113]
	v_mfma_f32_16x16x32_bf16 v[106:109], v[162:165], v[178:181], v[106:109]
	v_mfma_f32_16x16x32_bf16 v[94:97], v[134:137], v[186:189], v[94:97]
	v_mfma_f32_16x16x32_bf16 v[90:93], v[162:165], v[186:189], v[90:93]
	v_mfma_f32_16x16x32_bf16 v[78:81], v[134:137], v[194:197], v[78:81]
	v_mfma_f32_16x16x32_bf16 v[74:77], v[162:165], v[194:197], v[74:77]
	s_barrier
	s_add_i32 s18, 0, 0x1c000
	s_add_i32 s19, s26, s75
	v_add_u32_e32 v212, s18, v142
	v_lshl_add_u64 v[206:207], v[206:207], 0, s[82:83]
	s_mov_b32 m0, s19
	ds_read_b128 v[198:201], v212
	ds_read_b128 v[202:205], v212 offset:1024
	ds_read_b128 v[226:229], v212 offset:2048
	ds_read_b128 v[230:233], v212 offset:3072
	global_load_lds_dwordx4 v[206:207], off
	v_lshl_add_u64 v[206:207], v[234:235], 0, s[82:83]
	s_add_i32 m0, s19, 0x2000
	s_nop 0
	global_load_lds_dwordx4 v[206:207], off
	s_barrier
; #define LAS3 __attribute__((address_space(3)))
; template <class Epi>
; DI void gemm_phase(PG8_LAS unsigned char* lds, const Gemm g, const StaticOrder& S, const Epi& E) {
;     ...
;       PG8_LDB(B0, 1, 0); PG8_SCHED; PG8_LDA(At, 1, 0); PG8_STAGE(PG8_SA(0, 1), a2 + hstepA, voffA);
;       PG8_WAIT_L(8); PG8_BAR; PG8_WAIT_L(0); PG8_MMA(0, 0, At, B0); PG8_BAR; PG8_SCHED;
;       PG8_LDB(B1, 1, 1); PG8_STAGE(PG8_SB(1, 0), b3, voffB);
;       PG8_BAR; PG8_WAIT_L(0); PG8_MMA(0, 1, At, B1); PG8_BAR;
;       PG8_LDA(At, 1, 1); PG8_STAGE(PG8_SA(1, 0), a3, voffA);
;       PG8_BAR; PG8_WAIT_L(0); PG8_MMA(1, 0, At, B0); PG8_BAR; PG8_SCHED;
;       PG8_STAGE(PG8_SB(1, 1), b3 + hstepB, voffB);
;       PG8_WAIT_V(6); PG8_BAR; PG8_MMA(1, 1, At, B1); PG8_BAR;
;   DI void operator()(const f32x4 (&acc)[2][2][4][2], const pg8::Unit& un, int wr, int wc, int fr, int fq) const {
;     ...
;           const int c128 = upn * 256 + bj * 128;
;           const int col0 = c128 + wc * 32 + fq * 8;
;           f32x4 v0 = acc[ai][bj][m][0], v1 = acc[ai][bj][m][1];
;           if (MODE == 2) {
;             u32x4 w; w[0] = pk2(v0[0], v0[1]); w[1] = pk2(v0[2], v0[3]); w[2] = pk2(v1[0], v1[1]); w[3] = pk2(v1[2], v1[3]);
;             *(u32x4*)(u + (size_t)row * 1024 + col0) = w;
;           } else {
;             if (isA && !isctx && c128 < kend) {
;               f32x4 p0, p1;
; #pragma unroll
;               for (int e = 0; e < 4; ++e) { p0[e] = __shfl_xor(v0[e], 32); p1[e] = __shfl_xor(v1[e], 32); }
;               const int sp = row & 2047;
;               const int pos = (wc & 1) ? (sp & 63) : (sp >> 6);
;               LAS3 const float* tb = rope + (pos * 16 + 8 * (fq & 1)) * 2;
;               const f32x4 t0 = *(LAS3 const f32x4*)(tb), t1 = *(LAS3 const f32x4*)(tb + 4), t2 = *(LAS3 const f32x4*)(tb + 8), t3 = *(LAS3 const f32x4*)(tb + 12);
;               const float sg = (fq < 2) ? -1.f : 1.f;
;               v0[0] = v0[0] * t0[0] + sg * p0[0] * t0[1]; v0[1] = v0[1] * t0[2] + sg * p0[1] * t0[3];
;               v0[2] = v0[2] * t1[0] + sg * p0[2] * t1[1]; v0[3] = v0[3] * t1[2] + sg * p0[3] * t1[3];
;               v1[0] = v1[0] * t2[0] + sg * p1[0] * t2[1]; v1[1] = v1[1] * t2[2] + sg * p1[1] * t2[3];
;               v1[2] = v1[2] * t3[0] + sg * p1[2] * t3[1]; v1[3] = v1[3] * t3[2] + sg * p1[3] * t3[3];
;             }
;             if (c128 >= vend) {
; #pragma unroll
	s_waitcnt lgkmcnt(0)
	s_waitcnt lgkmcnt(0)
	v_mfma_f32_16x16x32_bf16 v[118:121], v[198:201], v[166:169], v[118:121]
	v_mfma_f32_16x16x32_bf16 v[114:117], v[226:229], v[166:169], v[114:117]
	v_mfma_f32_16x16x32_bf16 v[102:105], v[198:201], v[174:177], v[102:105]
	v_mfma_f32_16x16x32_bf16 v[98:101], v[226:229], v[174:177], v[98:101]
	v_mfma_f32_16x16x32_bf16 v[86:89], v[198:201], v[182:185], v[86:89]
	v_mfma_f32_16x16x32_bf16 v[82:85], v[226:229], v[182:185], v[82:85]
	v_mfma_f32_16x16x32_bf16 v[70:73], v[198:201], v[190:193], v[70:73]
	v_mfma_f32_16x16x32_bf16 v[66:69], v[226:229], v[190:193], v[66:69]
	v_mfma_f32_16x16x32_bf16 v[118:121], v[202:205], v[170:173], v[118:121]
	v_mfma_f32_16x16x32_bf16 v[114:117], v[230:233], v[170:173], v[114:117]
	v_mfma_f32_16x16x32_bf16 v[102:105], v[202:205], v[178:181], v[102:105]
	v_mfma_f32_16x16x32_bf16 v[98:101], v[230:233], v[178:181], v[98:101]
	v_mfma_f32_16x16x32_bf16 v[86:89], v[202:205], v[186:189], v[86:89]
	v_mfma_f32_16x16x32_bf16 v[82:85], v[230:233], v[186:189], v[82:85]
	v_mfma_f32_16x16x32_bf16 v[70:73], v[202:205], v[194:197], v[70:73]
	v_mfma_f32_16x16x32_bf16 v[66:69], v[230:233], v[194:197], v[66:69]
	s_mov_b32 m0, s96
	v_lshl_add_u64 v[206:207], v[236:237], 0, s[82:83]
	s_barrier
	ds_read_b128 v[166:169], v161 offset:49152
	ds_read_b128 v[170:173], v161 offset:50176
	ds_read_b128 v[174:177], v161 offset:51200
	ds_read_b128 v[178:181], v161 offset:52224
	ds_read_b128 v[182:185], v161 offset:53248
	ds_read_b128 v[186:189], v161 offset:54272
	ds_read_b128 v[190:193], v161 offset:55296
	ds_read_b128 v[194:197], v161 offset:56320
	global_load_lds_dwordx4 v[206:207], off
	v_lshl_add_u64 v[206:207], v[238:239], 0, s[82:83]
	s_mov_b32 m0, s97
	s_nop 0
	global_load_lds_dwordx4 v[206:207], off
	s_barrier
	s_waitcnt lgkmcnt(0)
	s_waitcnt lgkmcnt(0)
	v_mfma_f32_16x16x32_bf16 v[62:65], v[130:133], v[166:169], v[62:65]
	v_mfma_f32_16x16x32_bf16 v[58:61], v[156:159], v[166:169], v[58:61]
	v_mfma_f32_16x16x32_bf16 v[46:49], v[130:133], v[174:177], v[46:49]
	v_mfma_f32_16x16x32_bf16 v[42:45], v[156:159], v[174:177], v[42:45]
	v_mfma_f32_16x16x32_bf16 v[30:33], v[130:133], v[182:185], v[30:33]
	v_mfma_f32_16x16x32_bf16 v[26:29], v[156:159], v[182:185], v[26:29]
	v_mfma_f32_16x16x32_bf16 v[14:17], v[130:133], v[190:193], v[14:17]
	v_mfma_f32_16x16x32_bf16 v[10:13], v[156:159], v[190:193], v[10:13]
	v_mfma_f32_16x16x32_bf16 v[62:65], v[134:137], v[170:173], v[62:65]
	v_mfma_f32_16x16x32_bf16 v[58:61], v[162:165], v[170:173], v[58:61]
	v_mfma_f32_16x16x32_bf16 v[46:49], v[134:137], v[178:181], v[46:49]
	v_mfma_f32_16x16x32_bf16 v[42:45], v[162:165], v[178:181], v[42:45]
	v_mfma_f32_16x16x32_bf16 v[30:33], v[134:137], v[186:189], v[30:33]
	v_mfma_f32_16x16x32_bf16 v[26:29], v[162:165], v[186:189], v[26:29]
	v_mfma_f32_16x16x32_bf16 v[14:17], v[134:137], v[194:197], v[14:17]
	v_mfma_f32_16x16x32_bf16 v[10:13], v[162:165], v[194:197], v[10:13]
	s_barrier
	s_add_u32 s10, s10, 0x40080
	s_addc_u32 s11, s11, 0
	s_add_i32 s18, s18, s75
	v_lshl_add_u64 v[130:131], s[10:11], 0, v[0:1]
	s_mov_b32 m0, s18
	s_nop 0
	global_load_lds_dwordx4 v[130:131], off
	v_lshl_add_u64 v[130:131], s[10:11], 0, v[138:139]
	s_add_i32 m0, s18, 0x2000
	s_nop 0
	global_load_lds_dwordx4 v[130:131], off
	s_waitcnt vmcnt(6)
	s_barrier
	v_mfma_f32_16x16x32_bf16 v[54:57], v[198:201], v[166:169], v[54:57]
	v_mfma_f32_16x16x32_bf16 v[50:53], v[226:229], v[166:169], v[50:53]
	v_mfma_f32_16x16x32_bf16 v[38:41], v[198:201], v[174:177], v[38:41]
	v_mfma_f32_16x16x32_bf16 v[34:37], v[226:229], v[174:177], v[34:37]
	v_mfma_f32_16x16x32_bf16 v[22:25], v[198:201], v[182:185], v[22:25]
	v_mfma_f32_16x16x32_bf16 v[18:21], v[226:229], v[182:185], v[18:21]
	v_mfma_f32_16x16x32_bf16 v[6:9], v[198:201], v[190:193], v[6:9]
	v_mfma_f32_16x16x32_bf16 v[2:5], v[226:229], v[190:193], v[2:5]
	v_mfma_f32_16x16x32_bf16 v[54:57], v[202:205], v[170:173], v[54:57]
	v_mfma_f32_16x16x32_bf16 v[50:53], v[230:233], v[170:173], v[50:53]
	v_mfma_f32_16x16x32_bf16 v[38:41], v[202:205], v[178:181], v[38:41]
	v_mfma_f32_16x16x32_bf16 v[34:37], v[230:233], v[178:181], v[34:37]
	v_mfma_f32_16x16x32_bf16 v[22:25], v[202:205], v[186:189], v[22:25]
	v_mfma_f32_16x16x32_bf16 v[18:21], v[230:233], v[186:189], v[18:21]
	v_mfma_f32_16x16x32_bf16 v[6:9], v[202:205], v[194:197], v[6:9]
	v_mfma_f32_16x16x32_bf16 v[2:5], v[230:233], v[194:197], v[2:5]
	s_add_i32 s25, s25, 2
	s_add_u32 s8, s8, 0x100
	s_addc_u32 s9, s9, 0
	s_add_u32 s23, s23, 0x100
	s_addc_u32 s24, s24, 0
	s_cmp_gt_u32 s25, 13
	s_barrier
	s_cbranch_scc0 .LBB0_351
	s_cmp_lt_i32 s89, 8
	s_cselect_b64 s[10:11], -1, 0
	s_mov_b64 s[8:9], -1
	s_and_b64 vcc, exec, s[10:11]
	s_cbranch_vccz .LBB0_356
	v_mov_b64_e32 v[136:137], v[124:125]
	v_mov_b64_e32 v[132:133], v[128:129]
	s_cmp_gt_i32 s89, -1
	v_mov_b64_e32 v[134:135], v[122:123]
	v_mov_b64_e32 v[130:131], v[126:127]
	s_cbranch_scc1 .LBB0_355
	v_pk_mul_f32 v[132:133], v[128:129], s[94:95] op_sel_hi:[1,0]
	v_pk_mul_f32 v[130:131], v[126:127], s[94:95] op_sel_hi:[1,0]
	v_pk_mul_f32 v[136:137], v[124:125], s[94:95] op_sel_hi:[1,0]
	v_pk_mul_f32 v[134:135], v[122:123], s[94:95] op_sel_hi:[1,0]

; #define PG8_STAGE(bufoff, gbase, voff) do { _Pragma("unroll") for (int _i = 0; _i < 2; ++_i) \
;     __builtin_amdgcn_global_load_lds((const unsigned*)((const char*)(gbase) + (voff)[_i]), (PG8_LAS unsigned*)(lds + (bufoff) + ldsw + _i * 8192), 16, 0, 0); } while (0)
; #define PG8_LDA(dst, b, h) do { _Pragma("unroll") for (int m = 0; m < 4; ++m) _Pragma("unroll") for (int k = 0; k < 2; ++k) dst[m][k] = *(const PG8_LAS bf16x8*)(lds + PG8_SA(b, h) + aoff + m * 2048 + k * 1024); } while (0)
; #define PG8_LDB(dst, b, h) do { _Pragma("unroll") for (int n = 0; n < 2; ++n) _Pragma("unroll") for (int k = 0; k < 2; ++k) dst[n][k] = *(const PG8_LAS bf16x8*)(lds + PG8_SB(b, h) + boff + n * 2048 + k * 1024); } while (0)
; #define PG8_MMA(ai, bj, At, Bt) do { __builtin_amdgcn_s_setprio(1); _Pragma("unroll") for (int m = 0; m < 4; ++m) _Pragma("unroll") for (int n = 0; n < 2; ++n) _Pragma("unroll") for (int k = 0; k < 2; ++k) \
;     acc[ai][bj][m][n] = __builtin_amdgcn_mfma_f32_16x16x32_bf16(Bt[n][k], At[m][k], acc[ai][bj][m][n], 0, 0, 0); __builtin_amdgcn_s_setprio(0); } while (0)
; #define PG8_WAIT_V(n) asm volatile("s_waitcnt vmcnt(" #n ")" ::: "memory")
; template <class Epi>
; DI void gemm_phase(PG8_LAS unsigned char* lds, const Gemm g, const StaticOrder& S, const Epi& E) {
;     ...
;     for (int t = 0; t < nt; t += 2) {
;       const bool last = (t == nt - 2);
;       const char* a1 = cA + (size_t)(t + 1) * kstep;
;       const char* a2 = last ? nA : cA + (size_t)(t + 2) * kstep; const char* b2 = last ? nB : cB + (size_t)(t + 2) * kstep;
;       const char* a3 = a2 + kstep; const char* b3 = b2 + kstep;
;       PG8_LDB(B0, 0, 0); PG8_SCHED; PG8_LDA(At, 0, 0); PG8_STAGE(PG8_SA(1, 1), a1 + hstepA, voffA);
;       PG8_WAIT_L(8); PG8_BAR; PG8_WAIT_L(0); PG8_MMA(0, 0, At, B0); PG8_BAR; PG8_SCHED;
;       PG8_LDB(B1, 0, 1); PG8_STAGE(PG8_SB(0, 0), b2, voffB);
;       PG8_BAR; PG8_WAIT_L(0); PG8_MMA(0, 1, At, B1); PG8_BAR;
;       PG8_LDA(At, 0, 1); PG8_STAGE(PG8_SA(0, 0), a2, voffA);
;       PG8_BAR; PG8_WAIT_L(0); PG8_MMA(1, 0, At, B0); PG8_BAR; PG8_SCHED;
;       PG8_STAGE(PG8_SB(0, 1), b2 + hstepB, voffB);
;       PG8_WAIT_V(6); PG8_BAR; PG8_MMA(1, 1, At, B1); PG8_BAR;
;       PG8_LDB(B0, 1, 0); PG8_SCHED; PG8_LDA(At, 1, 0); PG8_STAGE(PG8_SA(0, 1), a2 + hstepA, voffA);
;       PG8_WAIT_L(8); PG8_BAR; PG8_WAIT_L(0); PG8_MMA(0, 0, At, B0); PG8_BAR; PG8_SCHED;
.LBB0_599:
	s_add_u32 s12, s10, 0xfffc0080
	s_addc_u32 s13, s11, -1
	s_add_i32 s25, 0, 0x10000
	v_add_u32_e32 v158, s25, v160
	ds_read_b128 v[130:133], v158
	ds_read_b128 v[134:137], v158 offset:1024
	ds_read_b128 v[166:169], v158 offset:2048
	ds_read_b128 v[170:173], v158 offset:3072
	s_cmp_eq_u32 s24, 12
	s_cselect_b32 s15, s17, s13
	s_cselect_b32 s14, s20, s12
	s_cselect_b32 s13, s1, s23
	s_cselect_b32 s12, s21, s22
	v_lshl_add_u64 v[158:159], s[10:11], 0, v[154:155]
	s_add_i32 m0, s87, 0xc000
	ds_read_b128 v[174:177], v165
	ds_read_b128 v[178:181], v165 offset:1024
	ds_read_b128 v[182:185], v165 offset:2048
	ds_read_b128 v[186:189], v165 offset:3072
	ds_read_b128 v[190:193], v165 offset:4096
	ds_read_b128 v[194:197], v165 offset:5120
	ds_read_b128 v[198:201], v165 offset:6144
	ds_read_b128 v[202:205], v165 offset:7168
	global_load_lds_dwordx4 v[158:159], off
	v_lshl_add_u64 v[158:159], s[10:11], 0, v[156:157]
	s_add_i32 m0, s87, 0xe000
	s_nop 0
	global_load_lds_dwordx4 v[158:159], off
	s_waitcnt lgkmcnt(8)
	s_barrier
	s_waitcnt lgkmcnt(0)
	s_waitcnt lgkmcnt(0)
	v_mfma_f32_16x16x32_bf16 v[126:129], v[130:133], v[174:177], v[126:129]
	v_mfma_f32_16x16x32_bf16 v[122:125], v[166:169], v[174:177], v[122:125]
	v_mfma_f32_16x16x32_bf16 v[110:113], v[130:133], v[182:185], v[110:113]
	v_mfma_f32_16x16x32_bf16 v[106:109], v[166:169], v[182:185], v[106:109]
	v_mfma_f32_16x16x32_bf16 v[94:97], v[130:133], v[190:193], v[94:97]
	v_mfma_f32_16x16x32_bf16 v[90:93], v[166:169], v[190:193], v[90:93]
	v_mfma_f32_16x16x32_bf16 v[78:81], v[130:133], v[198:201], v[78:81]
	v_mfma_f32_16x16x32_bf16 v[74:77], v[166:169], v[198:201], v[74:77]
	v_mfma_f32_16x16x32_bf16 v[126:129], v[134:137], v[178:181], v[126:129]
	v_mfma_f32_16x16x32_bf16 v[122:125], v[170:173], v[178:181], v[122:125]
	v_mfma_f32_16x16x32_bf16 v[110:113], v[134:137], v[186:189], v[110:113]
	v_mfma_f32_16x16x32_bf16 v[106:109], v[170:173], v[186:189], v[106:109]
	v_mfma_f32_16x16x32_bf16 v[94:97], v[134:137], v[194:197], v[94:97]
	v_mfma_f32_16x16x32_bf16 v[90:93], v[170:173], v[194:197], v[90:93]
	v_mfma_f32_16x16x32_bf16 v[78:81], v[134:137], v[202:205], v[78:81]
	v_mfma_f32_16x16x32_bf16 v[74:77], v[170:173], v[202:205], v[74:77]
	s_barrier
	s_add_i32 s33, 0, 0x14000
	v_add_u32_e32 v158, s33, v160
	s_add_i32 s25, s25, s75
	ds_read_b128 v[226:229], v158
	ds_read_b128 v[230:233], v158 offset:1024
	ds_read_b128 v[234:237], v158 offset:2048
	ds_read_b128 v[238:241], v158 offset:3072
	v_lshl_add_u64 v[158:159], s[12:13], 0, v[0:1]
	s_mov_b32 m0, s25
	v_lshl_add_u64 v[206:207], s[12:13], 0, v[138:139]
	global_load_lds_dwordx4 v[158:159], off
	s_add_i32 m0, s25, 0x2000
	s_nop 0
	global_load_lds_dwordx4 v[206:207], off
	s_barrier
	s_waitcnt lgkmcnt(0)
	s_waitcnt lgkmcnt(0)
	v_mfma_f32_16x16x32_bf16 v[118:121], v[226:229], v[174:177], v[118:121]
	v_mfma_f32_16x16x32_bf16 v[114:117], v[234:237], v[174:177], v[114:117]
	v_mfma_f32_16x16x32_bf16 v[102:105], v[226:229], v[182:185], v[102:105]
	v_mfma_f32_16x16x32_bf16 v[98:101], v[234:237], v[182:185], v[98:101]
	v_mfma_f32_16x16x32_bf16 v[86:89], v[226:229], v[190:193], v[86:89]
	v_mfma_f32_16x16x32_bf16 v[82:85], v[234:237], v[190:193], v[82:85]
	v_mfma_f32_16x16x32_bf16 v[70:73], v[226:229], v[198:201], v[70:73]
	v_mfma_f32_16x16x32_bf16 v[66:69], v[234:237], v[198:201], v[66:69]
	v_mfma_f32_16x16x32_bf16 v[118:121], v[230:233], v[178:181], v[118:121]
	v_mfma_f32_16x16x32_bf16 v[114:117], v[238:241], v[178:181], v[114:117]
	v_mfma_f32_16x16x32_bf16 v[102:105], v[230:233], v[186:189], v[102:105]
	v_mfma_f32_16x16x32_bf16 v[98:101], v[238:241], v[186:189], v[98:101]
	v_mfma_f32_16x16x32_bf16 v[86:89], v[230:233], v[194:197], v[86:89]
	v_mfma_f32_16x16x32_bf16 v[82:85], v[238:241], v[194:197], v[82:85]
	v_mfma_f32_16x16x32_bf16 v[70:73], v[230:233], v[202:205], v[70:73]
	v_mfma_f32_16x16x32_bf16 v[66:69], v[238:241], v[202:205], v[66:69]
	s_mov_b32 m0, s87
	v_lshl_add_u64 v[242:243], s[14:15], 0, v[148:149]
	s_barrier
	ds_read_b128 v[174:177], v165 offset:16384
	ds_read_b128 v[178:181], v165 offset:17408
	ds_read_b128 v[182:185], v165 offset:18432
	ds_read_b128 v[186:189], v165 offset:19456
	ds_read_b128 v[190:193], v165 offset:20480
	ds_read_b128 v[194:197], v165 offset:21504
	ds_read_b128 v[198:201], v165 offset:22528
	ds_read_b128 v[202:205], v165 offset:23552
	global_load_lds_dwordx4 v[242:243], off
	v_lshl_add_u64 v[244:245], s[14:15], 0, v[140:141]
	s_mov_b32 m0, s34
	s_nop 0
	global_load_lds_dwordx4 v[244:245], off
	s_barrier
	s_waitcnt lgkmcnt(0)
	s_waitcnt lgkmcnt(0)
	v_mfma_f32_16x16x32_bf16 v[62:65], v[130:133], v[174:177], v[62:65]
	v_mfma_f32_16x16x32_bf16 v[58:61], v[166:169], v[174:177], v[58:61]
	v_mfma_f32_16x16x32_bf16 v[46:49], v[130:133], v[182:185], v[46:49]
	v_mfma_f32_16x16x32_bf16 v[42:45], v[166:169], v[182:185], v[42:45]
	v_mfma_f32_16x16x32_bf16 v[30:33], v[130:133], v[190:193], v[30:33]
	v_mfma_f32_16x16x32_bf16 v[26:29], v[166:169], v[190:193], v[26:29]
	v_mfma_f32_16x16x32_bf16 v[14:17], v[130:133], v[198:201], v[14:17]
	v_mfma_f32_16x16x32_bf16 v[10:13], v[166:169], v[198:201], v[10:13]
	v_mfma_f32_16x16x32_bf16 v[62:65], v[134:137], v[178:181], v[62:65]
	v_mfma_f32_16x16x32_bf16 v[58:61], v[170:173], v[178:181], v[58:61]
	v_mfma_f32_16x16x32_bf16 v[46:49], v[134:137], v[186:189], v[46:49]
	v_mfma_f32_16x16x32_bf16 v[42:45], v[170:173], v[186:189], v[42:45]
	v_mfma_f32_16x16x32_bf16 v[30:33], v[134:137], v[194:197], v[30:33]
	v_mfma_f32_16x16x32_bf16 v[26:29], v[170:173], v[194:197], v[26:29]
	v_mfma_f32_16x16x32_bf16 v[14:17], v[134:137], v[202:205], v[14:17]
	v_mfma_f32_16x16x32_bf16 v[10:13], v[170:173], v[202:205], v[10:13]
	s_barrier
; #define PG8_STAGE(bufoff, gbase, voff) do { _Pragma("unroll") for (int _i = 0; _i < 2; ++_i) \
;     __builtin_amdgcn_global_load_lds((const unsigned*)((const char*)(gbase) + (voff)[_i]), (PG8_LAS unsigned*)(lds + (bufoff) + ldsw + _i * 8192), 16, 0, 0); } while (0)
; #define PG8_LDA(dst, b, h) do { _Pragma("unroll") for (int m = 0; m < 4; ++m) _Pragma("unroll") for (int k = 0; k < 2; ++k) dst[m][k] = *(const PG8_LAS bf16x8*)(lds + PG8_SA(b, h) + aoff + m * 2048 + k * 1024); } while (0)
; #define PG8_LDB(dst, b, h) do { _Pragma("unroll") for (int n = 0; n < 2; ++n) _Pragma("unroll") for (int k = 0; k < 2; ++k) dst[n][k] = *(const PG8_LAS bf16x8*)(lds + PG8_SB(b, h) + boff + n * 2048 + k * 1024); } while (0)
; #define PG8_MMA(ai, bj, At, Bt) do { __builtin_amdgcn_s_setprio(1); _Pragma("unroll") for (int m = 0; m < 4; ++m) _Pragma("unroll") for (int n = 0; n < 2; ++n) _Pragma("unroll") for (int k = 0; k < 2; ++k) \
;     acc[ai][bj][m][n] = __builtin_amdgcn_mfma_f32_16x16x32_bf16(Bt[n][k], At[m][k], acc[ai][bj][m][n], 0, 0, 0); __builtin_amdgcn_s_setprio(0); } while (0)
; #define PG8_WAIT_V(n) asm volatile("s_waitcnt vmcnt(" #n ")" ::: "memory")
; #define PG8_WAIT_L(n) asm volatile("s_waitcnt lgkmcnt(" #n ")" ::: "memory")
; #define PG8_BAR __builtin_amdgcn_s_barrier()
; #define PG8_SCHED __builtin_amdgcn_sched_barrier(0)
; template <class Epi>
; DI void gemm_phase(PG8_LAS unsigned char* lds, const Gemm g, const StaticOrder& S, const Epi& E) {
;     ...
;       PG8_BAR; PG8_WAIT_L(0); PG8_MMA(1, 0, At, B0); PG8_BAR; PG8_SCHED;
;       PG8_STAGE(PG8_SB(0, 1), b2 + hstepB, voffB);
;       PG8_WAIT_V(6); PG8_BAR; PG8_MMA(1, 1, At, B1); PG8_BAR;
;       PG8_LDB(B0, 1, 0); PG8_SCHED; PG8_LDA(At, 1, 0); PG8_STAGE(PG8_SA(0, 1), a2 + hstepA, voffA);
;       PG8_WAIT_L(8); PG8_BAR; PG8_WAIT_L(0); PG8_MMA(0, 0, At, B0); PG8_BAR; PG8_SCHED;
;       PG8_LDB(B1, 1, 1); PG8_STAGE(PG8_SB(1, 0), b3, voffB);
;       PG8_BAR; PG8_WAIT_L(0); PG8_MMA(0, 1, At, B1); PG8_BAR;
	s_add_u32 s26, s12, 0x40000
	s_addc_u32 s27, s13, 0
	s_add_i32 s25, s33, s75
	v_lshl_add_u64 v[130:131], s[26:27], 0, v[0:1]
	s_mov_b32 m0, s25
	s_nop 0
	global_load_lds_dwordx4 v[130:131], off
	v_lshl_add_u64 v[130:131], s[26:27], 0, v[138:139]
	s_add_i32 m0, s25, 0x2000
	s_nop 0
	global_load_lds_dwordx4 v[130:131], off
	s_waitcnt vmcnt(6)
	s_barrier
	v_mfma_f32_16x16x32_bf16 v[54:57], v[226:229], v[174:177], v[54:57]
	v_mfma_f32_16x16x32_bf16 v[50:53], v[234:237], v[174:177], v[50:53]
	v_mfma_f32_16x16x32_bf16 v[38:41], v[226:229], v[182:185], v[38:41]
	v_mfma_f32_16x16x32_bf16 v[34:37], v[234:237], v[182:185], v[34:37]
	v_mfma_f32_16x16x32_bf16 v[22:25], v[226:229], v[190:193], v[22:25]
	v_mfma_f32_16x16x32_bf16 v[18:21], v[234:237], v[190:193], v[18:21]
	v_mfma_f32_16x16x32_bf16 v[6:9], v[226:229], v[198:201], v[6:9]
	v_mfma_f32_16x16x32_bf16 v[2:5], v[234:237], v[198:201], v[2:5]
	v_mfma_f32_16x16x32_bf16 v[54:57], v[230:233], v[178:181], v[54:57]
	v_mfma_f32_16x16x32_bf16 v[50:53], v[238:241], v[178:181], v[50:53]
	v_mfma_f32_16x16x32_bf16 v[38:41], v[230:233], v[186:189], v[38:41]
	v_mfma_f32_16x16x32_bf16 v[34:37], v[238:241], v[186:189], v[34:37]
	v_mfma_f32_16x16x32_bf16 v[22:25], v[230:233], v[194:197], v[22:25]
	v_mfma_f32_16x16x32_bf16 v[18:21], v[238:241], v[194:197], v[18:21]
	v_mfma_f32_16x16x32_bf16 v[6:9], v[230:233], v[202:205], v[6:9]
	v_mfma_f32_16x16x32_bf16 v[2:5], v[238:241], v[202:205], v[2:5]
	s_add_i32 s25, 0, 0x18000
	v_add_u32_e32 v170, s25, v160
	s_barrier
	ds_read_b128 v[130:133], v170
	ds_read_b128 v[134:137], v170 offset:1024
	ds_read_b128 v[166:169], v170 offset:2048
	ds_read_b128 v[170:173], v170 offset:3072
	s_add_u32 s14, s14, 0x40000
	s_addc_u32 s15, s15, 0
	s_mov_b32 m0, s35
	v_lshl_add_u64 v[226:227], s[14:15], 0, v[148:149]
	ds_read_b128 v[174:177], v165 offset:32768
	ds_read_b128 v[178:181], v165 offset:33792
	ds_read_b128 v[182:185], v165 offset:34816
	ds_read_b128 v[186:189], v165 offset:35840
	ds_read_b128 v[190:193], v165 offset:36864
	ds_read_b128 v[194:197], v165 offset:37888
	ds_read_b128 v[198:201], v165 offset:38912
	ds_read_b128 v[202:205], v165 offset:39936
	global_load_lds_dwordx4 v[226:227], off
	v_lshl_add_u64 v[226:227], s[14:15], 0, v[140:141]
	s_mov_b32 m0, s84
	s_nop 0
	global_load_lds_dwordx4 v[226:227], off
	s_waitcnt lgkmcnt(8)
	s_barrier
	s_waitcnt lgkmcnt(0)
	s_waitcnt lgkmcnt(0)
	v_mfma_f32_16x16x32_bf16 v[126:129], v[130:133], v[174:177], v[126:129]
	v_mfma_f32_16x16x32_bf16 v[122:125], v[166:169], v[174:177], v[122:125]
	v_mfma_f32_16x16x32_bf16 v[110:113], v[130:133], v[182:185], v[110:113]
	v_mfma_f32_16x16x32_bf16 v[106:109], v[166:169], v[182:185], v[106:109]
	v_mfma_f32_16x16x32_bf16 v[94:97], v[130:133], v[190:193], v[94:97]
	v_mfma_f32_16x16x32_bf16 v[90:93], v[166:169], v[190:193], v[90:93]
	v_mfma_f32_16x16x32_bf16 v[78:81], v[130:133], v[198:201], v[78:81]
	v_mfma_f32_16x16x32_bf16 v[74:77], v[166:169], v[198:201], v[74:77]
	v_mfma_f32_16x16x32_bf16 v[126:129], v[134:137], v[178:181], v[126:129]
	v_mfma_f32_16x16x32_bf16 v[122:125], v[170:173], v[178:181], v[122:125]
	v_mfma_f32_16x16x32_bf16 v[110:113], v[134:137], v[186:189], v[110:113]
	v_mfma_f32_16x16x32_bf16 v[106:109], v[170:173], v[186:189], v[106:109]
	v_mfma_f32_16x16x32_bf16 v[94:97], v[134:137], v[194:197], v[94:97]
	v_mfma_f32_16x16x32_bf16 v[90:93], v[170:173], v[194:197], v[90:93]
	v_mfma_f32_16x16x32_bf16 v[78:81], v[134:137], v[202:205], v[78:81]
	v_mfma_f32_16x16x32_bf16 v[74:77], v[170:173], v[202:205], v[74:77]
	s_barrier
	s_add_i32 s14, 0, 0x1c000
	s_add_i32 s15, s25, s75
	v_add_u32_e32 v212, s14, v160
	v_lshl_add_u64 v[158:159], v[158:159], 0, s[82:83]
	s_mov_b32 m0, s15
	ds_read_b128 v[226:229], v212
	ds_read_b128 v[230:233], v212 offset:1024
	ds_read_b128 v[234:237], v212 offset:2048
	ds_read_b128 v[238:241], v212 offset:3072
	global_load_lds_dwordx4 v[158:159], off
	v_lshl_add_u64 v[158:159], v[206:207], 0, s[82:83]
	s_add_i32 m0, s15, 0x2000
	s_nop 0
	global_load_lds_dwordx4 v[158:159], off
	s_barrier
	s_waitcnt lgkmcnt(0)
	s_waitcnt lgkmcnt(0)
	v_mfma_f32_16x16x32_bf16 v[118:121], v[226:229], v[174:177], v[118:121]
	v_mfma_f32_16x16x32_bf16 v[114:117], v[234:237], v[174:177], v[114:117]
	v_mfma_f32_16x16x32_bf16 v[102:105], v[226:229], v[182:185], v[102:105]
	v_mfma_f32_16x16x32_bf16 v[98:101], v[234:237], v[182:185], v[98:101]
	v_mfma_f32_16x16x32_bf16 v[86:89], v[226:229], v[190:193], v[86:89]
	v_mfma_f32_16x16x32_bf16 v[82:85], v[234:237], v[190:193], v[82:85]
	v_mfma_f32_16x16x32_bf16 v[70:73], v[226:229], v[198:201], v[70:73]
	v_mfma_f32_16x16x32_bf16 v[66:69], v[234:237], v[198:201], v[66:69]
	v_mfma_f32_16x16x32_bf16 v[118:121], v[230:233], v[178:181], v[118:121]
	v_mfma_f32_16x16x32_bf16 v[114:117], v[238:241], v[178:181], v[114:117]
	v_mfma_f32_16x16x32_bf16 v[102:105], v[230:233], v[186:189], v[102:105]
	v_mfma_f32_16x16x32_bf16 v[98:101], v[238:241], v[186:189], v[98:101]
	v_mfma_f32_16x16x32_bf16 v[86:89], v[230:233], v[194:197], v[86:89]
	v_mfma_f32_16x16x32_bf16 v[82:85], v[238:241], v[194:197], v[82:85]
	v_mfma_f32_16x16x32_bf16 v[70:73], v[230:233], v[202:205], v[70:73]
	v_mfma_f32_16x16x32_bf16 v[66:69], v[238:241], v[202:205], v[66:69]
	s_mov_b32 m0, s78
	v_lshl_add_u64 v[158:159], v[242:243], 0, s[82:83]
	s_barrier
; #define LAS3 __attribute__((address_space(3)))
; #define PG8_STAGE(bufoff, gbase, voff) do { _Pragma("unroll") for (int _i = 0; _i < 2; ++_i) \
;     __builtin_amdgcn_global_load_lds((const unsigned*)((const char*)(gbase) + (voff)[_i]), (PG8_LAS unsigned*)(lds + (bufoff) + ldsw + _i * 8192), 16, 0, 0); } while (0)
; #define PG8_LDA(dst, b, h) do { _Pragma("unroll") for (int m = 0; m < 4; ++m) _Pragma("unroll") for (int k = 0; k < 2; ++k) dst[m][k] = *(const PG8_LAS bf16x8*)(lds + PG8_SA(b, h) + aoff + m * 2048 + k * 1024); } while (0)
; #define PG8_WAIT_V(n) asm volatile("s_waitcnt vmcnt(" #n ")" ::: "memory")
; #define PG8_WAIT_L(n) asm volatile("s_waitcnt lgkmcnt(" #n ")" ::: "memory")
; template <class Epi>
; DI void gemm_phase(PG8_LAS unsigned char* lds, const Gemm g, const StaticOrder& S, const Epi& E) {
;     ...
;       PG8_LDB(B1, 1, 1); PG8_STAGE(PG8_SB(1, 0), b3, voffB);
;       PG8_BAR; PG8_WAIT_L(0); PG8_MMA(0, 1, At, B1); PG8_BAR;
;       PG8_LDA(At, 1, 1); PG8_STAGE(PG8_SA(1, 0), a3, voffA);
;       PG8_BAR; PG8_WAIT_L(0); PG8_MMA(1, 0, At, B0); PG8_BAR; PG8_SCHED;
;       PG8_STAGE(PG8_SB(1, 1), b3 + hstepB, voffB);
;       PG8_WAIT_V(6); PG8_BAR; PG8_MMA(1, 1, At, B1); PG8_BAR;
;     }
;   DI void operator()(const f32x4 (&acc)[2][2][4][2], const pg8::Unit& un, int wr, int wc, int fr, int fq) const {
;     ...
;             if (isA && !isctx && c128 < kend) {
;               f32x4 p0, p1;
; #pragma unroll
;               for (int e = 0; e < 4; ++e) { p0[e] = __shfl_xor(v0[e], 32); p1[e] = __shfl_xor(v1[e], 32); }
;               const int sp = row & 2047;
;               const int pos = (wc & 1) ? (sp & 63) : (sp >> 6);
;               LAS3 const float* tb = rope + (pos * 16 + 8 * (fq & 1)) * 2;
;               const f32x4 t0 = *(LAS3 const f32x4*)(tb), t1 = *(LAS3 const f32x4*)(tb + 4), t2 = *(LAS3 const f32x4*)(tb + 8), t3 = *(LAS3 const f32x4*)(tb + 12);
;               const float sg = (fq < 2) ? -1.f : 1.f;
;               v0[0] = v0[0] * t0[0] + sg * p0[0] * t0[1]; v0[1] = v0[1] * t0[2] + sg * p0[1] * t0[3];
;               v0[2] = v0[2] * t1[0] + sg * p0[2] * t1[1]; v0[3] = v0[3] * t1[2] + sg * p0[3] * t1[3];
;               v1[0] = v1[0] * t2[0] + sg * p1[0] * t2[1]; v1[1] = v1[1] * t2[2] + sg * p1[1] * t2[3];
;               v1[2] = v1[2] * t3[0] + sg * p1[2] * t3[1]; v1[3] = v1[3] * t3[2] + sg * p1[3] * t3[3];
	ds_read_b128 v[174:177], v165 offset:49152
	ds_read_b128 v[178:181], v165 offset:50176
	ds_read_b128 v[182:185], v165 offset:51200
	ds_read_b128 v[186:189], v165 offset:52224
	ds_read_b128 v[190:193], v165 offset:53248
	ds_read_b128 v[194:197], v165 offset:54272
	ds_read_b128 v[198:201], v165 offset:55296
	ds_read_b128 v[202:205], v165 offset:56320
	global_load_lds_dwordx4 v[158:159], off
	v_lshl_add_u64 v[158:159], v[244:245], 0, s[82:83]
	s_mov_b32 m0, s85
	s_nop 0
	global_load_lds_dwordx4 v[158:159], off
	s_barrier
	s_waitcnt lgkmcnt(0)
	s_waitcnt lgkmcnt(0)
	v_mfma_f32_16x16x32_bf16 v[62:65], v[130:133], v[174:177], v[62:65]
	v_mfma_f32_16x16x32_bf16 v[58:61], v[166:169], v[174:177], v[58:61]
	v_mfma_f32_16x16x32_bf16 v[46:49], v[130:133], v[182:185], v[46:49]
	v_mfma_f32_16x16x32_bf16 v[42:45], v[166:169], v[182:185], v[42:45]
	v_mfma_f32_16x16x32_bf16 v[30:33], v[130:133], v[190:193], v[30:33]
	v_mfma_f32_16x16x32_bf16 v[26:29], v[166:169], v[190:193], v[26:29]
	v_mfma_f32_16x16x32_bf16 v[14:17], v[130:133], v[198:201], v[14:17]
	v_mfma_f32_16x16x32_bf16 v[10:13], v[166:169], v[198:201], v[10:13]
	v_mfma_f32_16x16x32_bf16 v[62:65], v[134:137], v[178:181], v[62:65]
	v_mfma_f32_16x16x32_bf16 v[58:61], v[170:173], v[178:181], v[58:61]
	v_mfma_f32_16x16x32_bf16 v[46:49], v[134:137], v[186:189], v[46:49]
	v_mfma_f32_16x16x32_bf16 v[42:45], v[170:173], v[186:189], v[42:45]
	v_mfma_f32_16x16x32_bf16 v[30:33], v[134:137], v[194:197], v[30:33]
	v_mfma_f32_16x16x32_bf16 v[26:29], v[170:173], v[194:197], v[26:29]
	v_mfma_f32_16x16x32_bf16 v[14:17], v[134:137], v[202:205], v[14:17]
	v_mfma_f32_16x16x32_bf16 v[10:13], v[170:173], v[202:205], v[10:13]
	s_barrier
	s_add_u32 s12, s12, 0x40080
	s_addc_u32 s13, s13, 0
	s_add_i32 s14, s14, s75
	v_lshl_add_u64 v[130:131], s[12:13], 0, v[0:1]
	s_mov_b32 m0, s14
	s_nop 0
	global_load_lds_dwordx4 v[130:131], off
	v_lshl_add_u64 v[130:131], s[12:13], 0, v[138:139]
	s_add_i32 m0, s14, 0x2000
	s_nop 0
	global_load_lds_dwordx4 v[130:131], off
	s_waitcnt vmcnt(6)
	s_barrier
	v_mfma_f32_16x16x32_bf16 v[54:57], v[226:229], v[174:177], v[54:57]
	v_mfma_f32_16x16x32_bf16 v[50:53], v[234:237], v[174:177], v[50:53]
	v_mfma_f32_16x16x32_bf16 v[38:41], v[226:229], v[182:185], v[38:41]
	v_mfma_f32_16x16x32_bf16 v[34:37], v[234:237], v[182:185], v[34:37]
	v_mfma_f32_16x16x32_bf16 v[22:25], v[226:229], v[190:193], v[22:25]
	v_mfma_f32_16x16x32_bf16 v[18:21], v[234:237], v[190:193], v[18:21]
	v_mfma_f32_16x16x32_bf16 v[6:9], v[226:229], v[198:201], v[6:9]
	v_mfma_f32_16x16x32_bf16 v[2:5], v[234:237], v[198:201], v[2:5]
	v_mfma_f32_16x16x32_bf16 v[54:57], v[230:233], v[178:181], v[54:57]
	v_mfma_f32_16x16x32_bf16 v[50:53], v[238:241], v[178:181], v[50:53]
	v_mfma_f32_16x16x32_bf16 v[38:41], v[230:233], v[186:189], v[38:41]
	v_mfma_f32_16x16x32_bf16 v[34:37], v[238:241], v[186:189], v[34:37]
	v_mfma_f32_16x16x32_bf16 v[22:25], v[230:233], v[194:197], v[22:25]
	v_mfma_f32_16x16x32_bf16 v[18:21], v[238:241], v[194:197], v[18:21]
	v_mfma_f32_16x16x32_bf16 v[6:9], v[230:233], v[202:205], v[6:9]
	v_mfma_f32_16x16x32_bf16 v[2:5], v[238:241], v[202:205], v[2:5]
	s_add_i32 s24, s24, 2
	s_add_u32 s10, s10, 0x100
	s_addc_u32 s11, s11, 0
	s_add_u32 s22, s22, 0x100
	s_addc_u32 s23, s23, 0
	s_cmp_gt_u32 s24, 13
	s_barrier
	s_cbranch_scc0 .LBB0_599
	s_cmpk_lt_i32 s16, 0x100
	s_cselect_b64 s[12:13], -1, 0
	s_lshl_b32 s97, s16, 8
	v_readlane_b32 s1, v255, 52
	s_add_i32 s97, s97, s1
	s_bfe_u32 s33, s97, 0x50006
	s_cmp_lt_i32 s86, 5
	v_mov_b32_e32 v130, s33
	s_cselect_b64 s[10:11], -1, 0
	v_cndmask_b32_e64 v130, v142, v130, s[6:7]
	s_and_b64 s[14:15], s[12:13], s[10:11]
	v_lshlrev_b32_e32 v130, 7, v130
	v_cndmask_b32_e64 v131, 0, 1, s[14:15]
	v_cmp_ne_u32_e64 s[10:11], 1, v131
	s_andn2_b64 vcc, exec, s[14:15]
	v_add_u32_e32 v166, v164, v130
	s_cbranch_vccnz .LBB0_602
	v_and_b32_e32 v131, 64, v214
	v_xor_b32_e32 v130, 32, v214
	v_add_u32_e32 v131, 64, v131
	v_cmp_lt_i32_e32 vcc, v130, v131
	s_nop 1
	v_cndmask_b32_e32 v130, v214, v130, vcc
	v_lshlrev_b32_e32 v134, 2, v130
	ds_bpermute_b32 v158, v134, v126
	ds_bpermute_b32 v159, v134, v127
	ds_read_b128 v[130:133], v166
	ds_bpermute_b32 v167, v134, v128
	ds_bpermute_b32 v181, v134, v129
	ds_bpermute_b32 v176, v134, v122
	ds_bpermute_b32 v177, v134, v123
	ds_bpermute_b32 v180, v134, v124
	ds_bpermute_b32 v182, v134, v125
	ds_read_b128 v[134:137], v166 offset:16
	ds_read_b128 v[168:171], v166 offset:32
	ds_read_b128 v[172:175], v166 offset:48
	s_waitcnt lgkmcnt(0)
	v_mov_b32_e32 v179, v132
	v_pk_mul_f32 v[158:159], v[152:153], v[158:159]
	v_mov_b32_e32 v132, v131
	v_mov_b32_e32 v178, v130
	v_pk_mul_f32 v[130:131], v[158:159], v[132:133]
	v_mul_f32_e32 v132, v152, v167
	v_mul_f32_e32 v128, v128, v134
	v_mul_f32_e32 v132, v132, v135
	v_mul_f32_e32 v135, v152, v181
	v_mov_b32_e32 v134, v129
	v_pk_mul_f32 v[134:135], v[134:135], v[136:137]
	v_mul_f32_e32 v137, v152, v182
	v_mov_b32_e32 v129, v134
	v_mov_b32_e32 v133, v135
	v_mov_b32_e32 v136, v125
	v_pk_fma_f32 v[126:127], v[126:127], v[178:179], v[130:131]
	v_pk_add_f32 v[128:129], v[128:129], v[132:133]
	v_mov_b32_e32 v131, v170
	v_pk_mul_f32 v[132:133], v[152:153], v[176:177]
	v_mov_b32_e32 v170, v169
	v_mul_f32_e32 v134, v152, v180
	v_pk_mul_f32 v[136:137], v[136:137], v[174:175]
	v_mov_b32_e32 v130, v168
	v_pk_mul_f32 v[132:133], v[132:133], v[170:171]
	v_mul_f32_e32 v124, v124, v172
	v_mul_f32_e32 v134, v134, v173
	v_mov_b32_e32 v125, v136
	v_mov_b32_e32 v135, v137
	v_pk_fma_f32 v[122:123], v[122:123], v[130:131], v[132:133]
	v_pk_add_f32 v[124:125], v[124:125], v[134:135]
